# in/out/down GEMM epilogue stores write-through (sc1) and their grid barriers skip the L2 writeback too
# baseline (speedup 1.0000x reference)
; __device__ __forceinline__ unsigned cvt_pk_bf16(float lo, float hi) { unsigned r; asm volatile("v_cvt_pk_bf16_f32 %0, %1, %2" : "=v"(r) : "v"(lo), "v"(hi)); return r; }
;     __device__ __forceinline__ void operator()(const f32x4 (&acc)[2][2][4][2], const Unit& u, int wr, int wc, int fr, int fq) const {
;     ...
;         for (int ai = 0; ai < 2; ++ai)
; #pragma unroll
;             for (int m = 0; m < 4; ++m) { bf16_t* rowp = O + (size_t)(row0 + ai * HALF + m * 16) * ldc + col0;
; #pragma unroll
;                 for (int bj = 0; bj < 2; ++bj) { const f32x4 v0 = acc[ai][bj][m][0], v1 = acc[ai][bj][m][1];
;                     u32x4 w; w.x = cvt_pk_bf16(v0[0], v0[1]); w.y = cvt_pk_bf16(v0[2], v0[3]); w.z = cvt_pk_bf16(v1[0], v1[1]); w.w = cvt_pk_bf16(v1[2], v1[3]);
;                     *(u32x4*)(rowp + bj * HALF) = w; } }
.LBB0_125:
	v_lshl_or_b32 v140, s34, 8, v144
	v_lshl_add_u32 v148, s35, 8, v142
	v_ashrrev_i32_e32 v141, 31, v140
	v_mov_b64_e32 v[138:139], s[84:85]
	v_mad_i64_i32 v[146:147], s[18:19], v148, s77, v[138:139]
	v_lshlrev_b64 v[140:141], 1, v[140:141]
	v_lshl_add_u64 v[146:147], v[146:147], 0, v[140:141]
	v_cvt_pk_bf16_f32 v124, v124, v125
	v_cvt_pk_bf16_f32 v125, v126, v127
	v_cvt_pk_bf16_f32 v126, v120, v121
	v_cvt_pk_bf16_f32 v127, v122, v123
	global_store_dwordx4 v[146:147], v[124:127], off sc1
	v_cvt_pk_bf16_f32 v112, v112, v113
	v_cvt_pk_bf16_f32 v113, v114, v115
	v_cvt_pk_bf16_f32 v114, v104, v105
	v_or_b32_e32 v104, 16, v148
	v_mad_i64_i32 v[104:105], s[18:19], v104, s77, v[138:139]
	v_cvt_pk_bf16_f32 v115, v106, v107
	global_store_dwordx4 v[146:147], v[112:115], off offset:256 sc1
	v_readlane_b32 s38, v255, 5
	v_readlane_b32 s40, v255, 7
	v_lshl_add_u64 v[112:113], v[104:105], 0, v[140:141]
	v_cvt_pk_bf16_f32 v104, v116, v117
	v_cvt_pk_bf16_f32 v105, v118, v119
	v_cvt_pk_bf16_f32 v106, v108, v109
	v_cvt_pk_bf16_f32 v107, v110, v111
	global_store_dwordx4 v[112:113], v[104:107], off sc1
	v_cvt_pk_bf16_f32 v96, v96, v97
	v_cvt_pk_bf16_f32 v97, v98, v99
	v_cvt_pk_bf16_f32 v98, v88, v89
	v_or_b32_e32 v88, 32, v148
	v_mad_i64_i32 v[88:89], s[18:19], v88, s77, v[138:139]
	v_cvt_pk_bf16_f32 v99, v90, v91
	global_store_dwordx4 v[112:113], v[96:99], off offset:256 sc1
	s_andn2_b64 vcc, exec, s[4:5]
	s_mov_b64 s[4:5], -1
	v_lshl_add_u64 v[96:97], v[88:89], 0, v[140:141]
	v_cvt_pk_bf16_f32 v88, v100, v101
	v_cvt_pk_bf16_f32 v89, v102, v103
	v_cvt_pk_bf16_f32 v90, v92, v93
	v_cvt_pk_bf16_f32 v91, v94, v95
	global_store_dwordx4 v[96:97], v[88:91], off sc1
	v_cvt_pk_bf16_f32 v80, v80, v81
	v_cvt_pk_bf16_f32 v81, v82, v83
	v_cvt_pk_bf16_f32 v82, v72, v73
	v_or_b32_e32 v72, 48, v148
	v_mad_i64_i32 v[72:73], s[18:19], v72, s77, v[138:139]
	v_cvt_pk_bf16_f32 v83, v74, v75
	global_store_dwordx4 v[96:97], v[80:83], off offset:256 sc1
	v_readlane_b32 s39, v255, 6
	v_readlane_b32 s41, v255, 8
	v_lshl_add_u64 v[80:81], v[72:73], 0, v[140:141]
	v_cvt_pk_bf16_f32 v72, v84, v85
	v_cvt_pk_bf16_f32 v73, v86, v87
	v_cvt_pk_bf16_f32 v74, v76, v77
	v_cvt_pk_bf16_f32 v75, v78, v79
	global_store_dwordx4 v[80:81], v[72:75], off sc1
	v_cvt_pk_bf16_f32 v68, v68, v69
	v_cvt_pk_bf16_f32 v69, v70, v71
	v_cvt_pk_bf16_f32 v70, v64, v65
	v_add_u32_e32 v64, 0x80, v148
	v_mad_i64_i32 v[64:65], s[18:19], v64, s77, v[138:139]
	v_lshl_add_u64 v[64:65], v[64:65], 0, v[140:141]
	v_cvt_pk_bf16_f32 v71, v66, v67
	global_store_dwordx4 v[80:81], v[68:71], off offset:256 sc1
	v_cvt_pk_bf16_f32 v60, v60, v61
	v_cvt_pk_bf16_f32 v61, v62, v63
	v_cvt_pk_bf16_f32 v62, v56, v57
	v_cvt_pk_bf16_f32 v63, v58, v59
	global_store_dwordx4 v[64:65], v[60:63], off sc1
	v_cvt_pk_bf16_f32 v48, v48, v49
	v_cvt_pk_bf16_f32 v49, v50, v51
	v_cvt_pk_bf16_f32 v50, v40, v41
	v_add_u32_e32 v40, 0x90, v148
	v_mad_i64_i32 v[40:41], s[18:19], v40, s77, v[138:139]
	v_cvt_pk_bf16_f32 v51, v42, v43
	global_store_dwordx4 v[64:65], v[48:51], off offset:256 sc1
	s_nop 1
	v_lshl_add_u64 v[48:49], v[40:41], 0, v[140:141]
	v_cvt_pk_bf16_f32 v40, v52, v53
	v_cvt_pk_bf16_f32 v41, v54, v55
	v_cvt_pk_bf16_f32 v42, v44, v45
	v_cvt_pk_bf16_f32 v43, v46, v47
	global_store_dwordx4 v[48:49], v[40:43], off sc1
	v_cvt_pk_bf16_f32 v32, v32, v33
	v_cvt_pk_bf16_f32 v33, v34, v35
	v_cvt_pk_bf16_f32 v34, v24, v25
	v_add_u32_e32 v24, 0xa0, v148
	v_mad_i64_i32 v[24:25], s[18:19], v24, s77, v[138:139]
	v_cvt_pk_bf16_f32 v35, v26, v27
	global_store_dwordx4 v[48:49], v[32:35], off offset:256 sc1
	s_nop 1
	v_lshl_add_u64 v[32:33], v[24:25], 0, v[140:141]
	v_cvt_pk_bf16_f32 v24, v36, v37
	v_cvt_pk_bf16_f32 v25, v38, v39
	v_cvt_pk_bf16_f32 v26, v28, v29
	v_cvt_pk_bf16_f32 v27, v30, v31
	global_store_dwordx4 v[32:33], v[24:27], off sc1
	v_cvt_pk_bf16_f32 v16, v16, v17
	v_cvt_pk_bf16_f32 v17, v18, v19
	v_cvt_pk_bf16_f32 v18, v8, v9
	v_add_u32_e32 v8, 0xb0, v148
	v_mad_i64_i32 v[8:9], s[18:19], v8, s77, v[138:139]
	v_cvt_pk_bf16_f32 v19, v10, v11
	global_store_dwordx4 v[32:33], v[16:19], off offset:256 sc1
	s_nop 1
	v_lshl_add_u64 v[16:17], v[8:9], 0, v[140:141]
	v_cvt_pk_bf16_f32 v8, v20, v21
	v_cvt_pk_bf16_f32 v9, v22, v23
	v_cvt_pk_bf16_f32 v10, v12, v13
	v_cvt_pk_bf16_f32 v11, v14, v15
	global_store_dwordx4 v[16:17], v[8:11], off sc1
	v_cvt_pk_bf16_f32 v4, v4, v5
	v_cvt_pk_bf16_f32 v5, v6, v7
	v_cvt_pk_bf16_f32 v6, v0, v1
	v_cvt_pk_bf16_f32 v7, v2, v3
	global_store_dwordx4 v[16:17], v[4:7], off offset:256 sc1
	s_cbranch_vccnz .LBB0_118
	s_andn2_b64 vcc, exec, s[6:7]
	s_cbranch_vccnz .LBB0_117
	s_barrier
	s_branch .LBB0_117

; #define LAS __attribute__((address_space(3)))
; DI unsigned pk2(float lo, float hi) { return f2bf(lo) | (f2bf(hi) << 16); }
; DI int permup(int n) { const int a = n >= DFF ? 1 : 0; const int ch = n - a * DFF; return (ch >> 7) * 256 + a * 128 + (ch & 127); }
; DI void p0_transpose_item(const float* W, int N, int k0, int n0, bf16* dst, int dst_ld, LAS float* scr, int lane) {
;     f32x4 v[8];
; #pragma unroll
;     for (int i = 0; i < 8; ++i) v[i] = __builtin_nontemporal_load((const f32x4*)(W + (size_t)(k0 + 8 * i + (lane >> 3)) * N + n0 + 4 * (lane & 7)));
; #pragma unroll
;     for (int i = 0; i < 8; ++i) { LAS float* q = scr + (8 * i + (lane >> 3)) * 33 + 4 * (lane & 7); q[0] = v[i].x; q[1] = v[i].y; q[2] = v[i].z; q[3] = v[i].w; }
;     asm volatile("s_waitcnt lgkmcnt(0)" ::: "memory");
;     const int c = lane & 7;
; #pragma unroll
;     for (int j = 0; j < 4; ++j) { const int n = (lane >> 3) + 8 * j; const LAS float* s = scr + (8 * c) * 33 + n;
;         v4u o; o.x = pk2(s[0 * 33], s[1 * 33]); o.y = pk2(s[2 * 33], s[3 * 33]); o.z = pk2(s[4 * 33], s[5 * 33]); o.w = pk2(s[6 * 33], s[7 * 33]);
; DI void p0_transposes(const Args& A, int wave_s, LAS unsigned char* lds, int it_lo, int it_hi, int widx, int nworkers) {
;     ...
;         const int l = it / I_L; int r = it % I_L;
;         if (r < I_IN) { const int kb = r / 96, nb = r % 96; p0_transpose_item(C.w_in + (size_t)l * 1024 * 3072, 3072, 64 * kb, 32 * nb, C.Win_t + (size_t)l * 3072 * 1024 + (size_t)(32 * nb) * 1024 + 64 * kb, 1024, scr, C.lane); continue; } r -= I_IN;
;         if (r < I_OUT) { const int kb = r / 32, nb = r % 32; p0_transpose_item(C.w_out + (size_t)l * 1024 * 1024, 1024, 64 * kb, 32 * nb, C.Wout_t + (size_t)l * 1024 * 1024 + (size_t)(32 * nb) * 1024 + 64 * kb, 1024, scr, C.lane); continue; } r -= I_OUT;
;         if (r < I_UP) { const int kb = r / 176, nb = r % 176; p0_transpose_item(C.w_up + (size_t)l * 1024 * 5632, 5632, 64 * kb, 32 * nb, C.Wup_t + (size_t)l * 5632 * 1024 + (size_t)permup(32 * nb) * 1024 + 64 * kb, 1024, scr, C.lane); continue; } r -= I_UP;
;         { const int kb = r / 32, nb = r % 32; const int k0 = 64 * kb;
;           p0_transpose_item(C.w_down + (size_t)l * 2816 * 1024, 1024, k0, 32 * nb, C.Wdn_t + (size_t)l * 2816 * 1024 + (size_t)(32 * nb) * DFF + k0, DFF, scr, C.lane); }
.LBB0_134:
	s_mul_hi_i32 s4, s11, 0x5397829d
	s_lshr_b32 s5, s4, 31
	s_ashr_i32 s4, s4, 11
	s_add_i32 s4, s4, s5
	s_mul_i32 s5, s4, 0xffffe780
	s_add_i32 s12, s11, s5
	s_cmpk_gt_i32 s12, 0x5ff
	s_mov_b64 s[6:7], -1
	s_cbranch_scc0 .LBB0_144
	s_cmpk_gt_u32 s12, 0x7ff
	s_cbranch_scc0 .LBB0_141
	s_cmpk_gt_u32 s12, 0x12ff
	s_cbranch_scc0 .LBB0_138
	s_mul_i32 s5, s4, 0xffffcf00
	s_add_i32 s5, s9, s5
	s_mul_i32 s6, s4, 0xb00
	s_and_b32 s5, s5, 0x7fffffc0
	s_ashr_i32 s7, s6, 31
	v_readlane_b32 s16, v252, 17
	s_add_i32 s96, s5, 0xffffda00
	s_lshl_b64 s[14:15], s[6:7], 12
	v_readlane_b32 s28, v252, 29
	v_readlane_b32 s29, v252, 30
	s_add_u32 s5, s28, s14
	s_addc_u32 s13, s29, s15
	s_and_b32 s14, s2, 0x3e0
	s_lshl_b64 s[6:7], s[6:7], 11
	v_readlane_b32 s15, v252, 54
	s_add_u32 s6, s15, s6
	v_readlane_b32 s15, v252, 55
	s_addc_u32 s7, s15, s7
	s_mul_i32 s15, s14, 0x1600
	s_add_u32 s15, s6, s15
	s_addc_u32 s16, s7, 0
	s_lshl_b64 s[6:7], s[96:97], 1
	s_add_u32 s6, s15, s6
	s_addc_u32 s7, s16, s7
	s_lshl_b32 s14, s14, 2
	v_add_u32_e32 v22, s96, v0
	s_add_u32 s14, s5, s14
	s_addc_u32 s15, s13, 0
	v_lshlrev_b32_e32 v160, 2, v2
	v_ashrrev_i32_e32 v23, 31, v22
	v_lshl_add_u64 v[24:25], s[14:15], 0, v[160:161]
	v_lshlrev_b64 v[22:23], 12, v[22:23]
	v_lshl_add_u64 v[52:53], v[24:25], 0, v[22:23]
	global_load_dwordx4 v[22:25], v[52:53], off nt
	v_add_co_u32_e32 v28, vcc, s33, v52
	s_mov_b32 s5, 0x10000
	s_nop 0
	v_addc_co_u32_e32 v29, vcc, 0, v53, vcc
	global_load_dwordx4 v[28:31], v[28:29], off nt
	v_add_co_u32_e32 v32, vcc, s5, v52
	s_mov_b32 s5, 0x18000
	s_nop 0
	v_addc_co_u32_e32 v33, vcc, 0, v53, vcc
	global_load_dwordx4 v[32:35], v[32:33], off nt
	v_add_co_u32_e32 v36, vcc, s5, v52
	s_mov_b32 s5, 0x20000
	s_nop 0
	v_addc_co_u32_e32 v37, vcc, 0, v53, vcc
	global_load_dwordx4 v[36:39], v[36:37], off nt
	v_add_co_u32_e32 v40, vcc, s5, v52
	v_add_u32_e32 v1, v3, v5
	s_nop 0
	v_addc_co_u32_e32 v41, vcc, 0, v53, vcc
	global_load_dwordx4 v[40:43], v[40:41], off nt
	v_add_co_u32_e32 v44, vcc, s57, v52
	v_add_u32_e32 v27, 0xc000, v1
	s_nop 0
	v_addc_co_u32_e32 v45, vcc, 0, v53, vcc
	global_load_dwordx4 v[44:47], v[44:45], off nt
	v_add_co_u32_e32 v48, vcc, s60, v52
	v_lshlrev_b32_e32 v160, 1, v4
	s_nop 0
	v_addc_co_u32_e32 v49, vcc, 0, v53, vcc
	global_load_dwordx4 v[48:51], v[48:49], off nt
	v_add_co_u32_e32 v52, vcc, s42, v52
	v_readlane_b32 s36, v255, 3
	s_nop 0
	v_addc_co_u32_e32 v53, vcc, 0, v53, vcc
	global_load_dwordx4 v[52:55], v[52:53], off nt
	v_readlane_b32 s17, v252, 18
	v_readlane_b32 s18, v252, 19
	v_readlane_b32 s19, v252, 20
	v_readlane_b32 s20, v252, 21
	v_readlane_b32 s21, v252, 22
	v_readlane_b32 s22, v252, 23
	v_readlane_b32 s23, v252, 24
	v_readlane_b32 s24, v252, 25
	v_readlane_b32 s25, v252, 26
	v_readlane_b32 s26, v252, 27
	v_readlane_b32 s27, v252, 28
	v_readlane_b32 s30, v252, 31
	v_readlane_b32 s31, v252, 32
	v_readlane_b32 s37, v255, 4
	s_waitcnt vmcnt(0)
	ds_write2_b32 v27, v22, v23 offset1:1
	v_add_u32_e32 v22, 0xc008, v1
	ds_write2_b32 v22, v24, v25 offset1:1
	v_add_u32_e32 v22, 0xc420, v1
	ds_write2_b32 v22, v28, v29 offset1:1
	v_add_u32_e32 v22, 0xc428, v1
	ds_write2_b32 v22, v30, v31 offset1:1
	v_add_u32_e32 v22, 0xc840, v1
	ds_write2_b32 v22, v32, v33 offset1:1
	v_add_u32_e32 v22, 0xc848, v1
	ds_write2_b32 v22, v34, v35 offset1:1
	v_add_u32_e32 v22, 0xcc60, v1
	ds_write2_b32 v22, v36, v37 offset1:1
	v_add_u32_e32 v22, 0xcc68, v1
	ds_write2_b32 v22, v38, v39 offset1:1
	v_add_u32_e32 v22, 0xd080, v1
	ds_write2_b32 v22, v40, v41 offset1:1
	v_add_u32_e32 v22, 0xd088, v1
	ds_write2_b32 v22, v42, v43 offset1:1
	v_add_u32_e32 v22, 0xd4a0, v1
	ds_write2_b32 v22, v44, v45 offset1:1
	v_add_u32_e32 v22, 0xd4a8, v1
	ds_write2_b32 v22, v46, v47 offset1:1
	v_add_u32_e32 v22, 0xd8c0, v1
	ds_write2_b32 v22, v48, v49 offset1:1
	v_add_u32_e32 v22, 0xd8c8, v1
	ds_write2_b32 v22, v50, v51 offset1:1
	v_add_u32_e32 v22, 0xdce0, v1
	v_add_u32_e32 v1, 0xdce8, v1
	ds_write2_b32 v22, v52, v53 offset1:1
	ds_write2_b32 v1, v54, v55 offset1:1
	s_waitcnt lgkmcnt(0)
	v_add_u32_e32 v1, 0xc000, v26
	ds_read2_b32 v[24:25], v1 offset0:33 offset1:41
	ds_read2_b32 v[32:33], v1 offset1:8
	ds_read2_b32 v[34:35], v1 offset0:66 offset1:74
	ds_read2_b32 v[36:37], v1 offset0:99 offset1:107
	ds_read2_b32 v[38:39], v1 offset0:132 offset1:140
	ds_read2_b32 v[40:41], v1 offset0:165 offset1:173
	ds_read2_b32 v[42:43], v1 offset0:198 offset1:206
	ds_read2_b32 v[44:45], v1 offset0:231 offset1:239
	s_waitcnt lgkmcnt(7)
	v_bfe_u32 v28, v24, 16, 1
	s_waitcnt lgkmcnt(6)
	v_bfe_u32 v27, v32, 16, 1
	v_add3_u32 v27, v32, v27, s79
	v_lshrrev_b32_e32 v27, 16, v27
	v_add3_u32 v24, v24, v28, s79
	v_and_or_b32 v28, v24, s82, v27
	s_waitcnt lgkmcnt(5)
	v_bfe_u32 v24, v34, 16, 1
	v_add3_u32 v24, v34, v24, s79
	s_waitcnt lgkmcnt(4)
	v_bfe_u32 v27, v36, 16, 1
	v_lshrrev_b32_e32 v24, 16, v24
	v_add3_u32 v27, v36, v27, s79
	v_and_or_b32 v29, v27, s82, v24
	s_waitcnt lgkmcnt(3)
	v_bfe_u32 v24, v38, 16, 1
	v_add3_u32 v24, v38, v24, s79
	s_waitcnt lgkmcnt(2)
	v_bfe_u32 v27, v40, 16, 1
	v_lshrrev_b32_e32 v24, 16, v24
	v_add3_u32 v27, v40, v27, s79
	v_and_or_b32 v30, v27, s82, v24
	s_waitcnt lgkmcnt(1)
	v_bfe_u32 v24, v42, 16, 1
	v_add3_u32 v24, v42, v24, s79
	s_waitcnt lgkmcnt(0)
; #define LAS __attribute__((address_space(3)))
; DI unsigned pk2(float lo, float hi) { return f2bf(lo) | (f2bf(hi) << 16); }
; DI int permup(int n) { const int a = n >= DFF ? 1 : 0; const int ch = n - a * DFF; return (ch >> 7) * 256 + a * 128 + (ch & 127); }
; DI void p0_transpose_item(const float* W, int N, int k0, int n0, bf16* dst, int dst_ld, LAS float* scr, int lane) {
;     ...
; #pragma unroll
;     for (int i = 0; i < 8; ++i) { LAS float* q = scr + (8 * i + (lane >> 3)) * 33 + 4 * (lane & 7); q[0] = v[i].x; q[1] = v[i].y; q[2] = v[i].z; q[3] = v[i].w; }
;     asm volatile("s_waitcnt lgkmcnt(0)" ::: "memory");
;     const int c = lane & 7;
; #pragma unroll
;     for (int j = 0; j < 4; ++j) { const int n = (lane >> 3) + 8 * j; const LAS float* s = scr + (8 * c) * 33 + n;
;         v4u o; o.x = pk2(s[0 * 33], s[1 * 33]); o.y = pk2(s[2 * 33], s[3 * 33]); o.z = pk2(s[4 * 33], s[5 * 33]); o.w = pk2(s[6 * 33], s[7 * 33]);
;         *(v4u*)(dst + (size_t)n * dst_ld + 8 * c) = o; }
; DI void p0_transposes(const Args& A, int wave_s, LAS unsigned char* lds, int it_lo, int it_hi, int widx, int nworkers) {
;     ...
;         if (r < I_UP) { const int kb = r / 176, nb = r % 176; p0_transpose_item(C.w_up + (size_t)l * 1024 * 5632, 5632, 64 * kb, 32 * nb, C.Wup_t + (size_t)l * 5632 * 1024 + (size_t)permup(32 * nb) * 1024 + 64 * kb, 1024, scr, C.lane); continue; } r -= I_UP;
	v_bfe_u32 v27, v44, 16, 1
	v_lshrrev_b32_e32 v24, 16, v24
	v_add3_u32 v27, v44, v27, s79
	v_and_or_b32 v31, v27, s82, v24
	v_bfe_u32 v24, v33, 16, 1
	v_lshl_add_u64 v[22:23], s[6:7], 0, v[160:161]
	v_add3_u32 v24, v33, v24, s79
	v_bfe_u32 v27, v25, 16, 1
	v_lshl_add_u64 v[46:47], v[22:23], 0, v[6:7]
	v_lshrrev_b32_e32 v24, 16, v24
	v_add3_u32 v25, v25, v27, s79
	global_store_dwordx4 v[46:47], v[28:31], off sc1
	v_lshl_add_u64 v[46:47], v[22:23], 0, v[10:11]
	s_mov_b64 s[6:7], 0
	v_and_or_b32 v28, v25, s82, v24
	v_bfe_u32 v24, v35, 16, 1
	v_add3_u32 v24, v35, v24, s79
	v_bfe_u32 v25, v37, 16, 1
	v_lshrrev_b32_e32 v24, 16, v24
	v_add3_u32 v25, v37, v25, s79
	v_and_or_b32 v29, v25, s82, v24
	v_bfe_u32 v24, v39, 16, 1
	v_add3_u32 v24, v39, v24, s79
	v_bfe_u32 v25, v41, 16, 1
	v_lshrrev_b32_e32 v24, 16, v24
	v_add3_u32 v25, v41, v25, s79
	v_and_or_b32 v30, v25, s82, v24
	v_bfe_u32 v24, v43, 16, 1
	v_add3_u32 v24, v43, v24, s79
	v_bfe_u32 v25, v45, 16, 1
	v_lshrrev_b32_e32 v24, 16, v24
	v_add3_u32 v25, v45, v25, s79
	v_and_or_b32 v31, v25, s82, v24
	v_lshl_add_u64 v[24:25], v[22:23], 0, v[8:9]
	global_store_dwordx4 v[24:25], v[28:31], off sc1
	ds_read2_b32 v[24:25], v1 offset0:49 offset1:57
	ds_read2_b32 v[32:33], v1 offset0:16 offset1:24
	ds_read2_b32 v[34:35], v1 offset0:82 offset1:90
	ds_read2_b32 v[36:37], v1 offset0:115 offset1:123
	ds_read2_b32 v[38:39], v1 offset0:148 offset1:156
	ds_read2_b32 v[40:41], v1 offset0:181 offset1:189
	ds_read2_b32 v[42:43], v1 offset0:214 offset1:222
	ds_read2_b32 v[44:45], v1 offset0:247 offset1:255
	s_waitcnt lgkmcnt(7)
	v_bfe_u32 v28, v24, 16, 1
	s_waitcnt lgkmcnt(6)
	v_bfe_u32 v27, v32, 16, 1
	v_add3_u32 v27, v32, v27, s79
	v_lshrrev_b32_e32 v27, 16, v27
	v_add3_u32 v24, v24, v28, s79
	v_and_or_b32 v28, v24, s82, v27
	s_waitcnt lgkmcnt(5)
	v_bfe_u32 v24, v34, 16, 1
	v_add3_u32 v24, v34, v24, s79
	s_waitcnt lgkmcnt(4)
	v_bfe_u32 v27, v36, 16, 1
	v_lshrrev_b32_e32 v24, 16, v24
	v_add3_u32 v27, v36, v27, s79
	v_and_or_b32 v29, v27, s82, v24
	s_waitcnt lgkmcnt(3)
	v_bfe_u32 v24, v38, 16, 1
	v_add3_u32 v24, v38, v24, s79
	s_waitcnt lgkmcnt(2)
	v_bfe_u32 v27, v40, 16, 1
	v_lshrrev_b32_e32 v24, 16, v24
	v_add3_u32 v27, v40, v27, s79
	s_waitcnt lgkmcnt(1)
	v_bfe_u32 v1, v42, 16, 1
	v_and_or_b32 v30, v27, s82, v24
	v_add3_u32 v1, v42, v1, s79
	s_waitcnt lgkmcnt(0)
	v_bfe_u32 v24, v44, 16, 1
	v_lshrrev_b32_e32 v1, 16, v1
	v_add3_u32 v24, v44, v24, s79
	v_and_or_b32 v31, v24, s82, v1
	v_bfe_u32 v1, v33, 16, 1
	v_add3_u32 v1, v33, v1, s79
	v_bfe_u32 v24, v25, 16, 1
	v_lshrrev_b32_e32 v1, 16, v1
	v_add3_u32 v24, v25, v24, s79
	global_store_dwordx4 v[46:47], v[28:31], off sc1
	v_lshl_add_u64 v[22:23], v[22:23], 0, v[12:13]
	s_nop 0
	v_and_or_b32 v28, v24, s82, v1
	v_bfe_u32 v1, v35, 16, 1
	v_add3_u32 v1, v35, v1, s79
	v_bfe_u32 v24, v37, 16, 1
	v_lshrrev_b32_e32 v1, 16, v1
	v_add3_u32 v24, v37, v24, s79
	v_and_or_b32 v29, v24, s82, v1
	v_bfe_u32 v1, v39, 16, 1
	v_add3_u32 v1, v39, v1, s79
	v_bfe_u32 v24, v41, 16, 1
	v_lshrrev_b32_e32 v1, 16, v1
	v_add3_u32 v24, v41, v24, s79
	v_and_or_b32 v30, v24, s82, v1
	v_bfe_u32 v1, v43, 16, 1
	v_add3_u32 v1, v43, v1, s79
	v_bfe_u32 v24, v45, 16, 1
	v_lshrrev_b32_e32 v1, 16, v1
	v_add3_u32 v24, v45, v24, s79
	v_and_or_b32 v31, v24, s82, v1
	global_store_dwordx4 v[22:23], v[28:31], off sc1
	s_waitcnt lgkmcnt(0)
.LBB0_138:
	s_andn2_b64 vcc, exec, s[6:7]
	s_cbranch_vccnz .LBB0_140
	s_add_i32 s5, s12, 0xf800
	s_and_b32 s6, s5, 0xffff
	s_mul_i32 s6, s6, 0xba2f
	v_readlane_b32 s16, v252, 17
	s_lshr_b32 s13, s6, 23
	v_readlane_b32 s17, v252, 18
	v_readlane_b32 s18, v252, 19
	v_readlane_b32 s19, v252, 20
	v_readlane_b32 s20, v252, 21
	v_readlane_b32 s21, v252, 22
	v_readlane_b32 s22, v252, 23
	v_readlane_b32 s23, v252, 24
	v_readlane_b32 s24, v252, 25
	v_readlane_b32 s25, v252, 26
	v_readlane_b32 s26, v252, 27
	v_readlane_b32 s27, v252, 28
	s_mul_i32 s6, s13, 0xb0
	v_readlane_b32 s28, v252, 29
	v_readlane_b32 s29, v252, 30
	v_readlane_b32 s30, v252, 31
	v_readlane_b32 s31, v252, 32
	s_mov_b64 s[16:17], s[20:21]
	s_sub_i32 s5, s5, s6
	s_mul_i32 s7, s4, 0x1600000
	s_mov_b64 s[18:19], s[22:23]
	s_mul_hi_i32 s6, s4, 0x1600000
	s_add_u32 s14, s18, s7
	s_addc_u32 s15, s19, s6
	s_lshl_b32 s6, s5, 5
	s_and_b32 s16, s6, 0xffe0
	s_mul_i32 s17, s4, 0xb00000
	v_readlane_b32 s18, v252, 52
	s_mul_hi_i32 s7, s4, 0xb00000
	s_add_u32 s17, s18, s17
	v_readlane_b32 s18, v252, 53
	s_addc_u32 s18, s18, s7
	s_and_b32 s5, s5, 0xffff
	s_cmpk_gt_u32 s5, 0x57
	s_cselect_b32 s5, 0xfffff500, 0
	s_cselect_b32 s7, 0x80, 0
	s_add_i32 s5, s5, s16
	s_lshl_b32 s5, s5, 1
	s_and_b32 s6, s6, 0x60
	s_and_b32 s5, s5, 0x7fffff00
	s_or_b32 s6, s6, s7
	s_or_b32 s96, s6, s5
	s_lshl_b64 s[6:7], s[96:97], 11
	s_add_u32 s5, s17, s6
	s_addc_u32 s7, s18, s7
	s_lshl_b32 s6, s13, 7
	s_add_u32 s6, s5, s6
	s_addc_u32 s7, s7, 0
	s_lshl_b32 s5, s16, 2
	s_add_u32 s14, s14, s5
	s_addc_u32 s15, s15, 0
	v_lshlrev_b32_e32 v160, 2, v2
	v_lshl_add_u32 v1, s13, 6, v0
	v_lshl_add_u64 v[52:53], s[14:15], 0, v[160:161]
	v_mad_i64_i32 v[22:23], s[14:15], v1, s43, v[52:53]
	global_load_dwordx4 v[22:25], v[22:23], off nt
	v_add_u32_e32 v27, 8, v1
	v_mad_i64_i32 v[28:29], s[14:15], v27, s43, v[52:53]
	global_load_dwordx4 v[28:31], v[28:29], off nt
	v_add_u32_e32 v27, 16, v1
	v_mad_i64_i32 v[32:33], s[14:15], v27, s43, v[52:53]
	global_load_dwordx4 v[32:35], v[32:33], off nt
	v_add_u32_e32 v27, 24, v1
	v_mad_i64_i32 v[36:37], s[14:15], v27, s43, v[52:53]
	global_load_dwordx4 v[36:39], v[36:37], off nt
	v_add_u32_e32 v27, 32, v1
	v_mad_i64_i32 v[40:41], s[14:15], v27, s43, v[52:53]
	global_load_dwordx4 v[40:43], v[40:41], off nt
	v_add_u32_e32 v27, 40, v1
	v_mad_i64_i32 v[44:45], s[14:15], v27, s43, v[52:53]
	global_load_dwordx4 v[44:47], v[44:45], off nt
	v_add_u32_e32 v27, 48, v1
	v_mad_i64_i32 v[48:49], s[14:15], v27, s43, v[52:53]
	global_load_dwordx4 v[48:51], v[48:49], off nt
	v_add_u32_e32 v1, 56, v1
	v_mad_i64_i32 v[52:53], s[14:15], v1, s43, v[52:53]
	global_load_dwordx4 v[52:55], v[52:53], off nt
	v_add_u32_e32 v1, v3, v5
	v_add_u32_e32 v27, 0xc000, v1
	v_lshlrev_b32_e32 v160, 1, v4
	v_readlane_b32 s36, v255, 3
	v_readlane_b32 s37, v255, 4
	s_mov_b64 s[20:21], s[24:25]
	s_mov_b64 s[22:23], s[26:27]
	s_mov_b64 s[24:25], s[28:29]
	s_mov_b64 s[26:27], s[30:31]
	s_waitcnt vmcnt(0)
; #define LAS __attribute__((address_space(3)))
; DI unsigned pk2(float lo, float hi) { return f2bf(lo) | (f2bf(hi) << 16); }
; DI void p0_transpose_item(const float* W, int N, int k0, int n0, bf16* dst, int dst_ld, LAS float* scr, int lane) {
;     ...
; #pragma unroll
;     for (int i = 0; i < 8; ++i) { LAS float* q = scr + (8 * i + (lane >> 3)) * 33 + 4 * (lane & 7); q[0] = v[i].x; q[1] = v[i].y; q[2] = v[i].z; q[3] = v[i].w; }
;     asm volatile("s_waitcnt lgkmcnt(0)" ::: "memory");
;     const int c = lane & 7;
; #pragma unroll
;     for (int j = 0; j < 4; ++j) { const int n = (lane >> 3) + 8 * j; const LAS float* s = scr + (8 * c) * 33 + n;
;         v4u o; o.x = pk2(s[0 * 33], s[1 * 33]); o.y = pk2(s[2 * 33], s[3 * 33]); o.z = pk2(s[4 * 33], s[5 * 33]); o.w = pk2(s[6 * 33], s[7 * 33]);
;         *(v4u*)(dst + (size_t)n * dst_ld + 8 * c) = o; }
;     asm volatile("s_waitcnt lgkmcnt(0)" ::: "memory");
; }
	ds_write2_b32 v27, v22, v23 offset1:1
	v_add_u32_e32 v22, 0xc008, v1
	ds_write2_b32 v22, v24, v25 offset1:1
	v_add_u32_e32 v22, 0xc420, v1
	ds_write2_b32 v22, v28, v29 offset1:1
	v_add_u32_e32 v22, 0xc428, v1
	ds_write2_b32 v22, v30, v31 offset1:1
	v_add_u32_e32 v22, 0xc840, v1
	ds_write2_b32 v22, v32, v33 offset1:1
	v_add_u32_e32 v22, 0xc848, v1
	ds_write2_b32 v22, v34, v35 offset1:1
	v_add_u32_e32 v22, 0xcc60, v1
	ds_write2_b32 v22, v36, v37 offset1:1
	v_add_u32_e32 v22, 0xcc68, v1
	ds_write2_b32 v22, v38, v39 offset1:1
	v_add_u32_e32 v22, 0xd080, v1
	ds_write2_b32 v22, v40, v41 offset1:1
	v_add_u32_e32 v22, 0xd088, v1
	ds_write2_b32 v22, v42, v43 offset1:1
	v_add_u32_e32 v22, 0xd4a0, v1
	ds_write2_b32 v22, v44, v45 offset1:1
	v_add_u32_e32 v22, 0xd4a8, v1
	ds_write2_b32 v22, v46, v47 offset1:1
	v_add_u32_e32 v22, 0xd8c0, v1
	ds_write2_b32 v22, v48, v49 offset1:1
	v_add_u32_e32 v22, 0xd8c8, v1
	ds_write2_b32 v22, v50, v51 offset1:1
	v_add_u32_e32 v22, 0xdce0, v1
	v_add_u32_e32 v1, 0xdce8, v1
	ds_write2_b32 v22, v52, v53 offset1:1
	ds_write2_b32 v1, v54, v55 offset1:1
	s_waitcnt lgkmcnt(0)
	v_add_u32_e32 v1, 0xc000, v26
	ds_read2_b32 v[24:25], v1 offset0:33 offset1:41
	ds_read2_b32 v[32:33], v1 offset1:8
	ds_read2_b32 v[34:35], v1 offset0:66 offset1:74
	ds_read2_b32 v[36:37], v1 offset0:99 offset1:107
	ds_read2_b32 v[38:39], v1 offset0:132 offset1:140
	ds_read2_b32 v[40:41], v1 offset0:165 offset1:173
	ds_read2_b32 v[42:43], v1 offset0:198 offset1:206
	ds_read2_b32 v[44:45], v1 offset0:231 offset1:239
	s_waitcnt lgkmcnt(7)
	v_bfe_u32 v28, v24, 16, 1
	s_waitcnt lgkmcnt(6)
	v_bfe_u32 v27, v32, 16, 1
	v_add3_u32 v27, v32, v27, s79
	v_lshrrev_b32_e32 v27, 16, v27
	v_add3_u32 v24, v24, v28, s79
	v_and_or_b32 v28, v24, s82, v27
	s_waitcnt lgkmcnt(5)
	v_bfe_u32 v24, v34, 16, 1
	v_add3_u32 v24, v34, v24, s79
	s_waitcnt lgkmcnt(4)
	v_bfe_u32 v27, v36, 16, 1
	v_lshrrev_b32_e32 v24, 16, v24
	v_add3_u32 v27, v36, v27, s79
	v_and_or_b32 v29, v27, s82, v24
	s_waitcnt lgkmcnt(3)
	v_bfe_u32 v24, v38, 16, 1
	v_add3_u32 v24, v38, v24, s79
	s_waitcnt lgkmcnt(2)
	v_bfe_u32 v27, v40, 16, 1
	v_lshrrev_b32_e32 v24, 16, v24
	v_add3_u32 v27, v40, v27, s79
	v_and_or_b32 v30, v27, s82, v24
	s_waitcnt lgkmcnt(1)
	v_bfe_u32 v24, v42, 16, 1
	v_add3_u32 v24, v42, v24, s79
	s_waitcnt lgkmcnt(0)
	v_bfe_u32 v27, v44, 16, 1
	v_lshrrev_b32_e32 v24, 16, v24
	v_add3_u32 v27, v44, v27, s79
	v_and_or_b32 v31, v27, s82, v24
	v_bfe_u32 v24, v33, 16, 1
	v_lshl_add_u64 v[22:23], s[6:7], 0, v[160:161]
	v_add3_u32 v24, v33, v24, s79
	v_bfe_u32 v27, v25, 16, 1
	v_lshl_add_u64 v[46:47], v[22:23], 0, v[14:15]
	v_lshrrev_b32_e32 v24, 16, v24
	v_add3_u32 v25, v25, v27, s79
	global_store_dwordx4 v[46:47], v[28:31], off sc1
	v_lshl_add_u64 v[46:47], v[22:23], 0, v[18:19]
	s_nop 0
	v_and_or_b32 v28, v25, s82, v24
	v_bfe_u32 v24, v35, 16, 1
	v_add3_u32 v24, v35, v24, s79
	v_bfe_u32 v25, v37, 16, 1
	v_lshrrev_b32_e32 v24, 16, v24
	v_add3_u32 v25, v37, v25, s79
	v_and_or_b32 v29, v25, s82, v24
	v_bfe_u32 v24, v39, 16, 1
	v_add3_u32 v24, v39, v24, s79
	v_bfe_u32 v25, v41, 16, 1
	v_lshrrev_b32_e32 v24, 16, v24
	v_add3_u32 v25, v41, v25, s79
	v_and_or_b32 v30, v25, s82, v24
	v_bfe_u32 v24, v43, 16, 1
	v_add3_u32 v24, v43, v24, s79
	v_bfe_u32 v25, v45, 16, 1
	v_lshrrev_b32_e32 v24, 16, v24
	v_add3_u32 v25, v45, v25, s79
	v_and_or_b32 v31, v25, s82, v24
	v_lshl_add_u64 v[24:25], v[22:23], 0, v[16:17]
	global_store_dwordx4 v[24:25], v[28:31], off sc1
	ds_read2_b32 v[24:25], v1 offset0:49 offset1:57
	ds_read2_b32 v[32:33], v1 offset0:16 offset1:24
	ds_read2_b32 v[34:35], v1 offset0:82 offset1:90
	ds_read2_b32 v[36:37], v1 offset0:115 offset1:123
	ds_read2_b32 v[38:39], v1 offset0:148 offset1:156
	ds_read2_b32 v[40:41], v1 offset0:181 offset1:189
	ds_read2_b32 v[42:43], v1 offset0:214 offset1:222
	ds_read2_b32 v[44:45], v1 offset0:247 offset1:255
	s_waitcnt lgkmcnt(7)
	v_bfe_u32 v28, v24, 16, 1
	s_waitcnt lgkmcnt(6)
	v_bfe_u32 v27, v32, 16, 1
	v_add3_u32 v27, v32, v27, s79
	v_lshrrev_b32_e32 v27, 16, v27
	v_add3_u32 v24, v24, v28, s79
	v_and_or_b32 v28, v24, s82, v27
	s_waitcnt lgkmcnt(5)
	v_bfe_u32 v24, v34, 16, 1
	v_add3_u32 v24, v34, v24, s79
	s_waitcnt lgkmcnt(4)
	v_bfe_u32 v27, v36, 16, 1
	v_lshrrev_b32_e32 v24, 16, v24
	v_add3_u32 v27, v36, v27, s79
	v_and_or_b32 v29, v27, s82, v24
	s_waitcnt lgkmcnt(3)
	v_bfe_u32 v24, v38, 16, 1
	v_add3_u32 v24, v38, v24, s79
	s_waitcnt lgkmcnt(2)
	v_bfe_u32 v27, v40, 16, 1
	v_lshrrev_b32_e32 v24, 16, v24
	v_add3_u32 v27, v40, v27, s79
	s_waitcnt lgkmcnt(1)
	v_bfe_u32 v1, v42, 16, 1
	v_and_or_b32 v30, v27, s82, v24
	v_add3_u32 v1, v42, v1, s79
	s_waitcnt lgkmcnt(0)
	v_bfe_u32 v24, v44, 16, 1
	v_lshrrev_b32_e32 v1, 16, v1
	v_add3_u32 v24, v44, v24, s79
	v_and_or_b32 v31, v24, s82, v1
	v_bfe_u32 v1, v33, 16, 1
	v_add3_u32 v1, v33, v1, s79
	v_bfe_u32 v24, v25, 16, 1
	v_lshrrev_b32_e32 v1, 16, v1
	v_add3_u32 v24, v25, v24, s79
	global_store_dwordx4 v[46:47], v[28:31], off sc1
	v_lshl_add_u64 v[22:23], v[22:23], 0, v[20:21]
	s_nop 0
	v_and_or_b32 v28, v24, s82, v1
	v_bfe_u32 v1, v35, 16, 1
	v_add3_u32 v1, v35, v1, s79
	v_bfe_u32 v24, v37, 16, 1
	v_lshrrev_b32_e32 v1, 16, v1
	v_add3_u32 v24, v37, v24, s79
	v_and_or_b32 v29, v24, s82, v1
	v_bfe_u32 v1, v39, 16, 1
	v_add3_u32 v1, v39, v1, s79
	v_bfe_u32 v24, v41, 16, 1
	v_lshrrev_b32_e32 v1, 16, v1
	v_add3_u32 v24, v41, v24, s79
	v_and_or_b32 v30, v24, s82, v1
	v_bfe_u32 v1, v43, 16, 1
	v_add3_u32 v1, v43, v1, s79
	v_bfe_u32 v24, v45, 16, 1
	v_lshrrev_b32_e32 v1, 16, v1
	v_add3_u32 v24, v45, v24, s79
	v_and_or_b32 v31, v24, s82, v1
	global_store_dwordx4 v[22:23], v[28:31], off sc1
	s_waitcnt lgkmcnt(0)

; #define LAS __attribute__((address_space(3)))
; DI unsigned pk2(float lo, float hi) { return f2bf(lo) | (f2bf(hi) << 16); }
; DI void p0_transpose_item(const float* W, int N, int k0, int n0, bf16* dst, int dst_ld, LAS float* scr, int lane) {
;     f32x4 v[8];
; #pragma unroll
;     for (int i = 0; i < 8; ++i) v[i] = __builtin_nontemporal_load((const f32x4*)(W + (size_t)(k0 + 8 * i + (lane >> 3)) * N + n0 + 4 * (lane & 7)));
; #pragma unroll
;     for (int i = 0; i < 8; ++i) { LAS float* q = scr + (8 * i + (lane >> 3)) * 33 + 4 * (lane & 7); q[0] = v[i].x; q[1] = v[i].y; q[2] = v[i].z; q[3] = v[i].w; }
;     asm volatile("s_waitcnt lgkmcnt(0)" ::: "memory");
;     const int c = lane & 7;
; #pragma unroll
;     for (int j = 0; j < 4; ++j) { const int n = (lane >> 3) + 8 * j; const LAS float* s = scr + (8 * c) * 33 + n;
;         v4u o; o.x = pk2(s[0 * 33], s[1 * 33]); o.y = pk2(s[2 * 33], s[3 * 33]); o.z = pk2(s[4 * 33], s[5 * 33]); o.w = pk2(s[6 * 33], s[7 * 33]);
; DI void p0_transposes(const Args& A, int wave_s, LAS unsigned char* lds, int it_lo, int it_hi, int widx, int nworkers) {
;     ...
;         if (r < I_OUT) { const int kb = r / 32, nb = r % 32; p0_transpose_item(C.w_out + (size_t)l * 1024 * 1024, 1024, 64 * kb, 32 * nb, C.Wout_t + (size_t)l * 1024 * 1024 + (size_t)(32 * nb) * 1024 + 64 * kb, 1024, scr, C.lane); continue; } r -= I_OUT;
.LBB0_141:
	s_andn2_b64 vcc, exec, s[6:7]
	s_cbranch_vccnz .LBB0_143
	v_readlane_b32 s16, v252, 17
	s_ashr_i32 s5, s4, 31
	v_readlane_b32 s17, v252, 18
	v_readlane_b32 s18, v252, 19
	v_readlane_b32 s19, v252, 20
	v_readlane_b32 s20, v252, 21
	v_readlane_b32 s21, v252, 22
	v_readlane_b32 s22, v252, 23
	v_readlane_b32 s23, v252, 24
	v_readlane_b32 s24, v252, 25
	v_readlane_b32 s25, v252, 26
	v_readlane_b32 s26, v252, 27
	v_readlane_b32 s27, v252, 28
	s_lshl_b64 s[6:7], s[4:5], 22
	v_readlane_b32 s28, v252, 29
	v_readlane_b32 s29, v252, 30
	v_readlane_b32 s30, v252, 31
	v_readlane_b32 s31, v252, 32
	s_mov_b64 s[16:17], s[20:21]
	s_add_u32 s13, s16, s6
	s_addc_u32 s15, s17, s7
	s_lshl_b32 s6, s4, 8
	s_sub_i32 s6, s9, s6
	s_and_b32 s6, s6, 0xfc0
	s_add_i32 s96, s6, 0xfffff400
	s_and_b32 s14, s2, 0x3e0
	s_lshl_b64 s[6:7], s[4:5], 21
	v_readlane_b32 s5, v252, 50
	s_add_u32 s5, s5, s6
	v_readlane_b32 s6, v252, 51
	s_addc_u32 s6, s6, s7
	s_lshl_b32 s7, s14, 11
	s_add_u32 s5, s5, s7
	s_addc_u32 s16, s6, 0
	s_lshl_b64 s[6:7], s[96:97], 1
	s_add_u32 s6, s5, s6
	s_addc_u32 s7, s16, s7
	s_lshl_b32 s5, s14, 2
	v_add_u32_e32 v22, s96, v0
	s_add_u32 s14, s13, s5
	s_addc_u32 s15, s15, 0
	v_lshlrev_b32_e32 v160, 2, v2
	v_ashrrev_i32_e32 v23, 31, v22
	v_lshl_add_u64 v[24:25], s[14:15], 0, v[160:161]
	v_lshlrev_b64 v[22:23], 12, v[22:23]
	v_lshl_add_u64 v[52:53], v[24:25], 0, v[22:23]
	global_load_dwordx4 v[22:25], v[52:53], off nt
	v_add_co_u32_e32 v28, vcc, s33, v52
	s_mov_b32 s5, 0x10000
	s_nop 0
	v_addc_co_u32_e32 v29, vcc, 0, v53, vcc
	global_load_dwordx4 v[28:31], v[28:29], off nt
	v_add_co_u32_e32 v32, vcc, s5, v52
	s_mov_b32 s5, 0x18000
	s_nop 0
	v_addc_co_u32_e32 v33, vcc, 0, v53, vcc
	global_load_dwordx4 v[32:35], v[32:33], off nt
	v_add_co_u32_e32 v36, vcc, s5, v52
	s_mov_b32 s5, 0x20000
	s_nop 0
	v_addc_co_u32_e32 v37, vcc, 0, v53, vcc
	global_load_dwordx4 v[36:39], v[36:37], off nt
	v_add_co_u32_e32 v40, vcc, s5, v52
	v_add_u32_e32 v1, v3, v5
	s_nop 0
	v_addc_co_u32_e32 v41, vcc, 0, v53, vcc
	global_load_dwordx4 v[40:43], v[40:41], off nt
	v_add_co_u32_e32 v44, vcc, s57, v52
	v_add_u32_e32 v27, 0xc000, v1
	s_nop 0
	v_addc_co_u32_e32 v45, vcc, 0, v53, vcc
	global_load_dwordx4 v[44:47], v[44:45], off nt
	v_add_co_u32_e32 v48, vcc, s60, v52
	v_lshlrev_b32_e32 v160, 1, v4
	s_nop 0
	v_addc_co_u32_e32 v49, vcc, 0, v53, vcc
	global_load_dwordx4 v[48:51], v[48:49], off nt
	v_add_co_u32_e32 v52, vcc, s42, v52
	v_readlane_b32 s36, v255, 3
	s_nop 0
	v_addc_co_u32_e32 v53, vcc, 0, v53, vcc
	global_load_dwordx4 v[52:55], v[52:53], off nt
	v_readlane_b32 s37, v255, 4
	s_mov_b64 s[18:19], s[22:23]
	s_mov_b64 s[20:21], s[24:25]
	s_mov_b64 s[22:23], s[26:27]
	s_mov_b64 s[24:25], s[28:29]
	s_mov_b64 s[26:27], s[30:31]
	s_waitcnt vmcnt(0)
	ds_write2_b32 v27, v22, v23 offset1:1
	v_add_u32_e32 v22, 0xc008, v1
	ds_write2_b32 v22, v24, v25 offset1:1
	v_add_u32_e32 v22, 0xc420, v1
	ds_write2_b32 v22, v28, v29 offset1:1
	v_add_u32_e32 v22, 0xc428, v1
	ds_write2_b32 v22, v30, v31 offset1:1
	v_add_u32_e32 v22, 0xc840, v1
	ds_write2_b32 v22, v32, v33 offset1:1
	v_add_u32_e32 v22, 0xc848, v1
	ds_write2_b32 v22, v34, v35 offset1:1
	v_add_u32_e32 v22, 0xcc60, v1
	ds_write2_b32 v22, v36, v37 offset1:1
	v_add_u32_e32 v22, 0xcc68, v1
	ds_write2_b32 v22, v38, v39 offset1:1
	v_add_u32_e32 v22, 0xd080, v1
	ds_write2_b32 v22, v40, v41 offset1:1
	v_add_u32_e32 v22, 0xd088, v1
	ds_write2_b32 v22, v42, v43 offset1:1
	v_add_u32_e32 v22, 0xd4a0, v1
	ds_write2_b32 v22, v44, v45 offset1:1
	v_add_u32_e32 v22, 0xd4a8, v1
	ds_write2_b32 v22, v46, v47 offset1:1
	v_add_u32_e32 v22, 0xd8c0, v1
	ds_write2_b32 v22, v48, v49 offset1:1
	v_add_u32_e32 v22, 0xd8c8, v1
	ds_write2_b32 v22, v50, v51 offset1:1
	v_add_u32_e32 v22, 0xdce0, v1
	v_add_u32_e32 v1, 0xdce8, v1
	ds_write2_b32 v22, v52, v53 offset1:1
	ds_write2_b32 v1, v54, v55 offset1:1
	s_waitcnt lgkmcnt(0)
	v_add_u32_e32 v1, 0xc000, v26
	ds_read2_b32 v[24:25], v1 offset0:33 offset1:41
	ds_read2_b32 v[32:33], v1 offset1:8
	ds_read2_b32 v[34:35], v1 offset0:66 offset1:74
	ds_read2_b32 v[36:37], v1 offset0:99 offset1:107
	ds_read2_b32 v[38:39], v1 offset0:132 offset1:140
	ds_read2_b32 v[40:41], v1 offset0:165 offset1:173
	ds_read2_b32 v[42:43], v1 offset0:198 offset1:206
	ds_read2_b32 v[44:45], v1 offset0:231 offset1:239
	s_waitcnt lgkmcnt(7)
; #define LAS __attribute__((address_space(3)))
; DI unsigned pk2(float lo, float hi) { return f2bf(lo) | (f2bf(hi) << 16); }
; DI void p0_transpose_item(const float* W, int N, int k0, int n0, bf16* dst, int dst_ld, LAS float* scr, int lane) {
;     ...
; #pragma unroll
;     for (int i = 0; i < 8; ++i) { LAS float* q = scr + (8 * i + (lane >> 3)) * 33 + 4 * (lane & 7); q[0] = v[i].x; q[1] = v[i].y; q[2] = v[i].z; q[3] = v[i].w; }
;     asm volatile("s_waitcnt lgkmcnt(0)" ::: "memory");
;     const int c = lane & 7;
; #pragma unroll
;     for (int j = 0; j < 4; ++j) { const int n = (lane >> 3) + 8 * j; const LAS float* s = scr + (8 * c) * 33 + n;
;         v4u o; o.x = pk2(s[0 * 33], s[1 * 33]); o.y = pk2(s[2 * 33], s[3 * 33]); o.z = pk2(s[4 * 33], s[5 * 33]); o.w = pk2(s[6 * 33], s[7 * 33]);
;         *(v4u*)(dst + (size_t)n * dst_ld + 8 * c) = o; }
;     asm volatile("s_waitcnt lgkmcnt(0)" ::: "memory");
	v_bfe_u32 v28, v24, 16, 1
	s_waitcnt lgkmcnt(6)
	v_bfe_u32 v27, v32, 16, 1
	v_add3_u32 v27, v32, v27, s79
	v_lshrrev_b32_e32 v27, 16, v27
	v_add3_u32 v24, v24, v28, s79
	v_and_or_b32 v28, v24, s82, v27
	s_waitcnt lgkmcnt(5)
	v_bfe_u32 v24, v34, 16, 1
	v_add3_u32 v24, v34, v24, s79
	s_waitcnt lgkmcnt(4)
	v_bfe_u32 v27, v36, 16, 1
	v_lshrrev_b32_e32 v24, 16, v24
	v_add3_u32 v27, v36, v27, s79
	v_and_or_b32 v29, v27, s82, v24
	s_waitcnt lgkmcnt(3)
	v_bfe_u32 v24, v38, 16, 1
	v_add3_u32 v24, v38, v24, s79
	s_waitcnt lgkmcnt(2)
	v_bfe_u32 v27, v40, 16, 1
	v_lshrrev_b32_e32 v24, 16, v24
	v_add3_u32 v27, v40, v27, s79
	v_and_or_b32 v30, v27, s82, v24
	s_waitcnt lgkmcnt(1)
	v_bfe_u32 v24, v42, 16, 1
	v_add3_u32 v24, v42, v24, s79
	s_waitcnt lgkmcnt(0)
	v_bfe_u32 v27, v44, 16, 1
	v_lshrrev_b32_e32 v24, 16, v24
	v_add3_u32 v27, v44, v27, s79
	v_and_or_b32 v31, v27, s82, v24
	v_bfe_u32 v24, v33, 16, 1
	v_lshl_add_u64 v[22:23], s[6:7], 0, v[160:161]
	v_add3_u32 v24, v33, v24, s79
	v_bfe_u32 v27, v25, 16, 1
	v_lshl_add_u64 v[46:47], v[22:23], 0, v[14:15]
	v_lshrrev_b32_e32 v24, 16, v24
	v_add3_u32 v25, v25, v27, s79
	global_store_dwordx4 v[46:47], v[28:31], off sc1
	v_lshl_add_u64 v[46:47], v[22:23], 0, v[18:19]
	s_nop 0
	v_and_or_b32 v28, v25, s82, v24
	v_bfe_u32 v24, v35, 16, 1
	v_add3_u32 v24, v35, v24, s79
	v_bfe_u32 v25, v37, 16, 1
	v_lshrrev_b32_e32 v24, 16, v24
	v_add3_u32 v25, v37, v25, s79
	v_and_or_b32 v29, v25, s82, v24
	v_bfe_u32 v24, v39, 16, 1
	v_add3_u32 v24, v39, v24, s79
	v_bfe_u32 v25, v41, 16, 1
	v_lshrrev_b32_e32 v24, 16, v24
	v_add3_u32 v25, v41, v25, s79
	v_and_or_b32 v30, v25, s82, v24
	v_bfe_u32 v24, v43, 16, 1
	v_add3_u32 v24, v43, v24, s79
	v_bfe_u32 v25, v45, 16, 1
	v_lshrrev_b32_e32 v24, 16, v24
	v_add3_u32 v25, v45, v25, s79
	v_and_or_b32 v31, v25, s82, v24
	v_lshl_add_u64 v[24:25], v[22:23], 0, v[16:17]
	global_store_dwordx4 v[24:25], v[28:31], off sc1
	ds_read2_b32 v[24:25], v1 offset0:49 offset1:57
	ds_read2_b32 v[32:33], v1 offset0:16 offset1:24
	ds_read2_b32 v[34:35], v1 offset0:82 offset1:90
	ds_read2_b32 v[36:37], v1 offset0:115 offset1:123
	ds_read2_b32 v[38:39], v1 offset0:148 offset1:156
	ds_read2_b32 v[40:41], v1 offset0:181 offset1:189
	ds_read2_b32 v[42:43], v1 offset0:214 offset1:222
	ds_read2_b32 v[44:45], v1 offset0:247 offset1:255
	s_waitcnt lgkmcnt(7)
	v_bfe_u32 v28, v24, 16, 1
	s_waitcnt lgkmcnt(6)
	v_bfe_u32 v27, v32, 16, 1
	v_add3_u32 v27, v32, v27, s79
	v_lshrrev_b32_e32 v27, 16, v27
	v_add3_u32 v24, v24, v28, s79
	v_and_or_b32 v28, v24, s82, v27
	s_waitcnt lgkmcnt(5)
	v_bfe_u32 v24, v34, 16, 1
	v_add3_u32 v24, v34, v24, s79
	s_waitcnt lgkmcnt(4)
	v_bfe_u32 v27, v36, 16, 1
	v_lshrrev_b32_e32 v24, 16, v24
	v_add3_u32 v27, v36, v27, s79
	v_and_or_b32 v29, v27, s82, v24
	s_waitcnt lgkmcnt(3)
	v_bfe_u32 v24, v38, 16, 1
	v_add3_u32 v24, v38, v24, s79
	s_waitcnt lgkmcnt(2)
	v_bfe_u32 v27, v40, 16, 1
	v_lshrrev_b32_e32 v24, 16, v24
	v_add3_u32 v27, v40, v27, s79
	s_waitcnt lgkmcnt(1)
	v_bfe_u32 v1, v42, 16, 1
	v_and_or_b32 v30, v27, s82, v24
	v_add3_u32 v1, v42, v1, s79
	s_waitcnt lgkmcnt(0)
	v_bfe_u32 v24, v44, 16, 1
	v_lshrrev_b32_e32 v1, 16, v1
	v_add3_u32 v24, v44, v24, s79
	v_and_or_b32 v31, v24, s82, v1
	v_bfe_u32 v1, v33, 16, 1
	v_add3_u32 v1, v33, v1, s79
	v_bfe_u32 v24, v25, 16, 1
	v_lshrrev_b32_e32 v1, 16, v1
	v_add3_u32 v24, v25, v24, s79
	global_store_dwordx4 v[46:47], v[28:31], off sc1
	v_lshl_add_u64 v[22:23], v[22:23], 0, v[20:21]
	s_nop 0
	v_and_or_b32 v28, v24, s82, v1
	v_bfe_u32 v1, v35, 16, 1
	v_add3_u32 v1, v35, v1, s79
	v_bfe_u32 v24, v37, 16, 1
	v_lshrrev_b32_e32 v1, 16, v1
	v_add3_u32 v24, v37, v24, s79
	v_and_or_b32 v29, v24, s82, v1
	v_bfe_u32 v1, v39, 16, 1
	v_add3_u32 v1, v39, v1, s79
	v_bfe_u32 v24, v41, 16, 1
	v_lshrrev_b32_e32 v1, 16, v1
	v_add3_u32 v24, v41, v24, s79
	v_and_or_b32 v30, v24, s82, v1
	v_bfe_u32 v1, v43, 16, 1
	v_add3_u32 v1, v43, v1, s79
	v_bfe_u32 v24, v45, 16, 1
	v_lshrrev_b32_e32 v1, 16, v1
	v_add3_u32 v24, v45, v24, s79
	v_and_or_b32 v31, v24, s82, v1
	global_store_dwordx4 v[22:23], v[28:31], off sc1
	s_waitcnt lgkmcnt(0)

; #define LAS __attribute__((address_space(3)))
; DI unsigned pk2(float lo, float hi) { return f2bf(lo) | (f2bf(hi) << 16); }
; DI void p0_transpose_item(const float* W, int N, int k0, int n0, bf16* dst, int dst_ld, LAS float* scr, int lane) {
;     f32x4 v[8];
; #pragma unroll
;     for (int i = 0; i < 8; ++i) v[i] = __builtin_nontemporal_load((const f32x4*)(W + (size_t)(k0 + 8 * i + (lane >> 3)) * N + n0 + 4 * (lane & 7)));
; #pragma unroll
;     for (int i = 0; i < 8; ++i) { LAS float* q = scr + (8 * i + (lane >> 3)) * 33 + 4 * (lane & 7); q[0] = v[i].x; q[1] = v[i].y; q[2] = v[i].z; q[3] = v[i].w; }
;     asm volatile("s_waitcnt lgkmcnt(0)" ::: "memory");
;     const int c = lane & 7;
; #pragma unroll
;     for (int j = 0; j < 4; ++j) { const int n = (lane >> 3) + 8 * j; const LAS float* s = scr + (8 * c) * 33 + n;
;         v4u o; o.x = pk2(s[0 * 33], s[1 * 33]); o.y = pk2(s[2 * 33], s[3 * 33]); o.z = pk2(s[4 * 33], s[5 * 33]); o.w = pk2(s[6 * 33], s[7 * 33]);
; DI void p0_transposes(const Args& A, int wave_s, LAS unsigned char* lds, int it_lo, int it_hi, int widx, int nworkers) {
;     ...
;         if (r < I_IN) { const int kb = r / 96, nb = r % 96; p0_transpose_item(C.w_in + (size_t)l * 1024 * 3072, 3072, 64 * kb, 32 * nb, C.Win_t + (size_t)l * 3072 * 1024 + (size_t)(32 * nb) * 1024 + 64 * kb, 1024, scr, C.lane); continue; } r -= I_IN;
.LBB0_144:
	s_andn2_b64 vcc, exec, s[6:7]
	s_cbranch_vccnz .LBB0_133
	s_mul_i32 s5, s12, 0x2aab
	s_lshr_b32 s6, s5, 31
	s_ashr_i32 s5, s5, 20
	s_add_i32 s5, s5, s6
	s_sext_i32_i16 s6, s5
	s_mulk_i32 s5, 0x60
	s_sub_i32 s5, s12, s5
	s_mul_i32 s12, s4, 0xc00000
	v_readlane_b32 s16, v252, 1
	s_sext_i32_i16 s5, s5
	s_mul_hi_i32 s7, s4, 0xc00000
	v_readlane_b32 s17, v252, 2
	s_add_u32 s14, s16, s12
	s_addc_u32 s15, s17, s7
	s_lshl_b32 s6, s6, 6
	s_lshl_b32 s12, s5, 5
	s_mul_hi_i32 s5, s4, 0x600000
	s_mul_i32 s4, s4, 0x600000
	s_add_u32 s7, s70, s4
	s_addc_u32 s16, s69, s5
	s_ashr_i32 s13, s12, 31
	s_lshl_b64 s[4:5], s[12:13], 11
	s_add_u32 s17, s7, s4
	s_addc_u32 s16, s16, s5
	s_ashr_i32 s7, s6, 31
	s_lshl_b64 s[4:5], s[6:7], 1
	s_add_u32 s4, s17, s4
	s_addc_u32 s5, s16, s5
	v_add_u32_e32 v1, s6, v0
	s_lshl_b64 s[6:7], s[12:13], 2
	s_add_u32 s6, s14, s6
	s_addc_u32 s7, s15, s7
	v_lshlrev_b32_e32 v160, 2, v2
	v_lshl_add_u64 v[52:53], s[6:7], 0, v[160:161]
	v_mad_i64_i32 v[22:23], s[6:7], v1, s44, v[52:53]
	global_load_dwordx4 v[22:25], v[22:23], off nt
	v_add_u32_e32 v27, 8, v1
	v_mad_i64_i32 v[28:29], s[6:7], v27, s44, v[52:53]
	global_load_dwordx4 v[28:31], v[28:29], off nt
	v_add_u32_e32 v27, 16, v1
	v_mad_i64_i32 v[32:33], s[6:7], v27, s44, v[52:53]
	global_load_dwordx4 v[32:35], v[32:33], off nt
	v_add_u32_e32 v27, 24, v1
	v_mad_i64_i32 v[36:37], s[6:7], v27, s44, v[52:53]
	global_load_dwordx4 v[36:39], v[36:37], off nt
	v_add_u32_e32 v27, 32, v1
	v_mad_i64_i32 v[40:41], s[6:7], v27, s44, v[52:53]
	global_load_dwordx4 v[40:43], v[40:41], off nt
	v_add_u32_e32 v27, 40, v1
	v_mad_i64_i32 v[44:45], s[6:7], v27, s44, v[52:53]
	global_load_dwordx4 v[44:47], v[44:45], off nt
	v_add_u32_e32 v27, 48, v1
	v_mad_i64_i32 v[48:49], s[6:7], v27, s44, v[52:53]
	global_load_dwordx4 v[48:51], v[48:49], off nt
	v_add_u32_e32 v1, 56, v1
	v_mad_i64_i32 v[52:53], s[6:7], v1, s44, v[52:53]
	global_load_dwordx4 v[52:55], v[52:53], off nt
	v_add_u32_e32 v1, v3, v5
	v_add_u32_e32 v27, 0xc000, v1
	v_lshlrev_b32_e32 v160, 1, v4
	v_readlane_b32 s18, v252, 3
	v_readlane_b32 s19, v252, 4
	v_readlane_b32 s20, v252, 5
	v_readlane_b32 s21, v252, 6
	v_readlane_b32 s22, v252, 7
	v_readlane_b32 s23, v252, 8
	v_readlane_b32 s24, v252, 9
	v_readlane_b32 s25, v252, 10
	v_readlane_b32 s26, v252, 11
	v_readlane_b32 s27, v252, 12
	v_readlane_b32 s28, v252, 13
	v_readlane_b32 s29, v252, 14
	v_readlane_b32 s30, v252, 15
	v_readlane_b32 s31, v252, 16
	s_waitcnt vmcnt(0)
	ds_write2_b32 v27, v22, v23 offset1:1
	v_add_u32_e32 v22, 0xc008, v1
	ds_write2_b32 v22, v24, v25 offset1:1
	v_add_u32_e32 v22, 0xc420, v1
	ds_write2_b32 v22, v28, v29 offset1:1
	v_add_u32_e32 v22, 0xc428, v1
	ds_write2_b32 v22, v30, v31 offset1:1
	v_add_u32_e32 v22, 0xc840, v1
	ds_write2_b32 v22, v32, v33 offset1:1
	v_add_u32_e32 v22, 0xc848, v1
	ds_write2_b32 v22, v34, v35 offset1:1
	v_add_u32_e32 v22, 0xcc60, v1
	ds_write2_b32 v22, v36, v37 offset1:1
	v_add_u32_e32 v22, 0xcc68, v1
	ds_write2_b32 v22, v38, v39 offset1:1
	v_add_u32_e32 v22, 0xd080, v1
	ds_write2_b32 v22, v40, v41 offset1:1
	v_add_u32_e32 v22, 0xd088, v1
	ds_write2_b32 v22, v42, v43 offset1:1
	v_add_u32_e32 v22, 0xd4a0, v1
	ds_write2_b32 v22, v44, v45 offset1:1
	v_add_u32_e32 v22, 0xd4a8, v1
	ds_write2_b32 v22, v46, v47 offset1:1
	v_add_u32_e32 v22, 0xd8c0, v1
	ds_write2_b32 v22, v48, v49 offset1:1
	v_add_u32_e32 v22, 0xd8c8, v1
	ds_write2_b32 v22, v50, v51 offset1:1
	v_add_u32_e32 v22, 0xdce0, v1
	v_add_u32_e32 v1, 0xdce8, v1
	ds_write2_b32 v22, v52, v53 offset1:1
	ds_write2_b32 v1, v54, v55 offset1:1
	s_waitcnt lgkmcnt(0)
	v_add_u32_e32 v1, 0xc000, v26
	ds_read2_b32 v[24:25], v1 offset0:33 offset1:41
	ds_read2_b32 v[32:33], v1 offset1:8
	ds_read2_b32 v[34:35], v1 offset0:66 offset1:74
	ds_read2_b32 v[36:37], v1 offset0:99 offset1:107
	ds_read2_b32 v[38:39], v1 offset0:132 offset1:140
	ds_read2_b32 v[40:41], v1 offset0:165 offset1:173
	ds_read2_b32 v[42:43], v1 offset0:198 offset1:206
	ds_read2_b32 v[44:45], v1 offset0:231 offset1:239
	s_waitcnt lgkmcnt(7)
	v_bfe_u32 v28, v24, 16, 1
	s_waitcnt lgkmcnt(6)
; #define LAS __attribute__((address_space(3)))
; DI unsigned pk2(float lo, float hi) { return f2bf(lo) | (f2bf(hi) << 16); }
; DI void p0_transpose_item(const float* W, int N, int k0, int n0, bf16* dst, int dst_ld, LAS float* scr, int lane) {
;     ...
; #pragma unroll
;     for (int i = 0; i < 8; ++i) { LAS float* q = scr + (8 * i + (lane >> 3)) * 33 + 4 * (lane & 7); q[0] = v[i].x; q[1] = v[i].y; q[2] = v[i].z; q[3] = v[i].w; }
;     asm volatile("s_waitcnt lgkmcnt(0)" ::: "memory");
;     const int c = lane & 7;
; #pragma unroll
;     for (int j = 0; j < 4; ++j) { const int n = (lane >> 3) + 8 * j; const LAS float* s = scr + (8 * c) * 33 + n;
;         v4u o; o.x = pk2(s[0 * 33], s[1 * 33]); o.y = pk2(s[2 * 33], s[3 * 33]); o.z = pk2(s[4 * 33], s[5 * 33]); o.w = pk2(s[6 * 33], s[7 * 33]);
;         *(v4u*)(dst + (size_t)n * dst_ld + 8 * c) = o; }
;     asm volatile("s_waitcnt lgkmcnt(0)" ::: "memory");
; }
	v_bfe_u32 v27, v32, 16, 1
	v_add3_u32 v27, v32, v27, s79
	v_lshrrev_b32_e32 v27, 16, v27
	v_add3_u32 v24, v24, v28, s79
	v_and_or_b32 v28, v24, s82, v27
	s_waitcnt lgkmcnt(5)
	v_bfe_u32 v24, v34, 16, 1
	v_add3_u32 v24, v34, v24, s79
	s_waitcnt lgkmcnt(4)
	v_bfe_u32 v27, v36, 16, 1
	v_lshrrev_b32_e32 v24, 16, v24
	v_add3_u32 v27, v36, v27, s79
	v_and_or_b32 v29, v27, s82, v24
	s_waitcnt lgkmcnt(3)
	v_bfe_u32 v24, v38, 16, 1
	v_add3_u32 v24, v38, v24, s79
	s_waitcnt lgkmcnt(2)
	v_bfe_u32 v27, v40, 16, 1
	v_lshrrev_b32_e32 v24, 16, v24
	v_add3_u32 v27, v40, v27, s79
	v_and_or_b32 v30, v27, s82, v24
	s_waitcnt lgkmcnt(1)
	v_bfe_u32 v24, v42, 16, 1
	v_add3_u32 v24, v42, v24, s79
	s_waitcnt lgkmcnt(0)
	v_bfe_u32 v27, v44, 16, 1
	v_lshrrev_b32_e32 v24, 16, v24
	v_add3_u32 v27, v44, v27, s79
	v_and_or_b32 v31, v27, s82, v24
	v_bfe_u32 v24, v33, 16, 1
	v_lshl_add_u64 v[22:23], s[4:5], 0, v[160:161]
	v_add3_u32 v24, v33, v24, s79
	v_bfe_u32 v27, v25, 16, 1
	v_lshl_add_u64 v[46:47], v[22:23], 0, v[14:15]
	v_lshrrev_b32_e32 v24, 16, v24
	v_add3_u32 v25, v25, v27, s79
	global_store_dwordx4 v[46:47], v[28:31], off sc1
	v_lshl_add_u64 v[46:47], v[22:23], 0, v[18:19]
	s_nop 0
	v_and_or_b32 v28, v25, s82, v24
	v_bfe_u32 v24, v35, 16, 1
	v_add3_u32 v24, v35, v24, s79
	v_bfe_u32 v25, v37, 16, 1
	v_lshrrev_b32_e32 v24, 16, v24
	v_add3_u32 v25, v37, v25, s79
	v_and_or_b32 v29, v25, s82, v24
	v_bfe_u32 v24, v39, 16, 1
	v_add3_u32 v24, v39, v24, s79
	v_bfe_u32 v25, v41, 16, 1
	v_lshrrev_b32_e32 v24, 16, v24
	v_add3_u32 v25, v41, v25, s79
	v_and_or_b32 v30, v25, s82, v24
	v_bfe_u32 v24, v43, 16, 1
	v_add3_u32 v24, v43, v24, s79
	v_bfe_u32 v25, v45, 16, 1
	v_lshrrev_b32_e32 v24, 16, v24
	v_add3_u32 v25, v45, v25, s79
	v_and_or_b32 v31, v25, s82, v24
	v_lshl_add_u64 v[24:25], v[22:23], 0, v[16:17]
	global_store_dwordx4 v[24:25], v[28:31], off sc1
	ds_read2_b32 v[24:25], v1 offset0:49 offset1:57
	ds_read2_b32 v[32:33], v1 offset0:16 offset1:24
	ds_read2_b32 v[34:35], v1 offset0:82 offset1:90
	ds_read2_b32 v[36:37], v1 offset0:115 offset1:123
	ds_read2_b32 v[38:39], v1 offset0:148 offset1:156
	ds_read2_b32 v[40:41], v1 offset0:181 offset1:189
	ds_read2_b32 v[42:43], v1 offset0:214 offset1:222
	ds_read2_b32 v[44:45], v1 offset0:247 offset1:255
	s_waitcnt lgkmcnt(7)
	v_bfe_u32 v28, v24, 16, 1
	s_waitcnt lgkmcnt(6)
	v_bfe_u32 v27, v32, 16, 1
	v_add3_u32 v27, v32, v27, s79
	v_lshrrev_b32_e32 v27, 16, v27
	v_add3_u32 v24, v24, v28, s79
	v_and_or_b32 v28, v24, s82, v27
	s_waitcnt lgkmcnt(5)
	v_bfe_u32 v24, v34, 16, 1
	v_add3_u32 v24, v34, v24, s79
	s_waitcnt lgkmcnt(4)
	v_bfe_u32 v27, v36, 16, 1
	v_lshrrev_b32_e32 v24, 16, v24
	v_add3_u32 v27, v36, v27, s79
	v_and_or_b32 v29, v27, s82, v24
	s_waitcnt lgkmcnt(3)
	v_bfe_u32 v24, v38, 16, 1
	v_add3_u32 v24, v38, v24, s79
	s_waitcnt lgkmcnt(2)
	v_bfe_u32 v27, v40, 16, 1
	v_lshrrev_b32_e32 v24, 16, v24
	v_add3_u32 v27, v40, v27, s79
	s_waitcnt lgkmcnt(1)
	v_bfe_u32 v1, v42, 16, 1
	v_and_or_b32 v30, v27, s82, v24
	v_add3_u32 v1, v42, v1, s79
	s_waitcnt lgkmcnt(0)
	v_bfe_u32 v24, v44, 16, 1
	v_lshrrev_b32_e32 v1, 16, v1
	v_add3_u32 v24, v44, v24, s79
	v_and_or_b32 v31, v24, s82, v1
	v_bfe_u32 v1, v33, 16, 1
	v_add3_u32 v1, v33, v1, s79
	v_bfe_u32 v24, v25, 16, 1
	v_lshrrev_b32_e32 v1, 16, v1
	v_add3_u32 v24, v25, v24, s79
	global_store_dwordx4 v[46:47], v[28:31], off sc1
	v_lshl_add_u64 v[22:23], v[22:23], 0, v[20:21]
	s_nop 0
	v_and_or_b32 v28, v24, s82, v1
	v_bfe_u32 v1, v35, 16, 1
	v_add3_u32 v1, v35, v1, s79
	v_bfe_u32 v24, v37, 16, 1
	v_lshrrev_b32_e32 v1, 16, v1
	v_add3_u32 v24, v37, v24, s79
	v_and_or_b32 v29, v24, s82, v1
	v_bfe_u32 v1, v39, 16, 1
	v_add3_u32 v1, v39, v1, s79
	v_bfe_u32 v24, v41, 16, 1
	v_lshrrev_b32_e32 v1, 16, v1
	v_add3_u32 v24, v41, v24, s79
	v_and_or_b32 v30, v24, s82, v1
	v_bfe_u32 v1, v43, 16, 1
	v_add3_u32 v1, v43, v1, s79
	v_bfe_u32 v24, v45, 16, 1
	v_lshrrev_b32_e32 v1, 16, v1
	v_add3_u32 v24, v45, v24, s79
	v_and_or_b32 v31, v24, s82, v1
	global_store_dwordx4 v[22:23], v[28:31], off sc1
	s_waitcnt lgkmcnt(0)
	s_branch .LBB0_133

; __device__ __forceinline__ unsigned xb_ld(unsigned* p)              { return __hip_atomic_load(p, __ATOMIC_RELAXED, __HIP_MEMORY_SCOPE_AGENT); }
; __device__ __forceinline__ unsigned xb_add(unsigned* p, unsigned v) { return __hip_atomic_fetch_add(p, v, __ATOMIC_RELAXED, __HIP_MEMORY_SCOPE_AGENT); }
; #define XB_SPIN(cond, bar) do { unsigned _sp = 0; while (cond) { __builtin_amdgcn_s_sleep(1); \
;     if ((++_sp & 255u) == 0u) { if (xb_ld(&(bar)[XB_TMO])) break; if (_sp > XB_SPIN_CAP) { atomicAdd(&(bar)[XB_TMO], 1u); break; } } } } while (0)
; __device__ __forceinline__ void xcd_barrier(const XcdBarrier& b, int xtid) {
;     asm volatile("s_waitcnt vmcnt(0)" ::: "memory");
;     __syncthreads();
;     if (xtid == 0) {
;         unsigned* bar = b.bar; unsigned bx_ = b.x; asm volatile("" : "+s"(bx_));
;         __builtin_amdgcn_s_waitcnt(0);
;         unsigned nloc = b.st[0], nx = b.st[1];
;         if (nloc == 0u) { xcd_barrier_complete(bar, bx_, nloc, nx); b.st[0] = nloc; b.st[1] = nx; }
;         const unsigned old = xb_add(&bar[XB_XSUB(bx_)], 1u);
;         const unsigned gen = old / nloc;
;         if (old + 1u == (gen + 1u) * nloc) {
;             __builtin_amdgcn_fence(__ATOMIC_RELEASE, "agent");
;             asm volatile("s_waitcnt vmcnt(0)" ::: "memory");
;             const unsigned og = xb_add(&bar[XB_TOP], 1u);
;             const unsigned tg = og / nx;
;             if (og + 1u == (tg + 1u) * nx) xb_add(&bar[XB_TOPGEN], 1u);
;             else XB_SPIN(xb_ld(&bar[XB_TOPGEN]) == tg, bar);
;             __builtin_amdgcn_fence(__ATOMIC_ACQUIRE, "agent");
;             xb_add(&bar[XB_XGEN(bx_)], 1u);
;             asm volatile("s_waitcnt vmcnt(0)" ::: "memory");
;         } else {
;             XB_SPIN(xb_ld(&bar[XB_XGEN(bx_)]) == gen, bar);
;             __builtin_amdgcn_fence(__ATOMIC_ACQUIRE, "agent");
;             asm volatile("s_waitcnt vmcnt(0)" ::: "memory");
;         }
.LBB0_178:
	s_andn2_saveexec_b64 s[6:7], s[6:7]
	s_cbranch_execz .LBB0_198
	s_mov_b64 s[6:7], exec
	s_nop 0
	s_waitcnt lgkmcnt(0)
	s_waitcnt vmcnt(0)
	v_mbcnt_lo_u32_b32 v1, s6, 0
	v_mbcnt_hi_u32_b32 v1, s7, v1
	v_cmp_eq_u32_e32 vcc, 0, v1
	s_and_saveexec_b64 s[8:9], vcc
	s_cbranch_execz .LBB0_181
	s_bcnt1_i32_b64 s6, s[6:7]
	v_mov_b32_e32 v2, s6
	v_readlane_b32 s6, v253, 8
	v_readlane_b32 s7, v253, 9
	s_nop 4
	global_atomic_add v2, v161, v2, s[6:7] sc0
.LBB0_181:
	s_or_b64 exec, exec, s[8:9]
	s_waitcnt vmcnt(0)
	v_readfirstlane_b32 s6, v2
	v_cvt_f32_u32_e32 v2, v0
	v_sub_u32_e32 v3, 0, v0
	v_add_u32_e32 v1, s6, v1
	v_readlane_b32 s6, v253, 10
	v_rcp_iflag_f32_e32 v2, v2
	v_readlane_b32 s7, v253, 11
	s_mov_b64 s[8:9], -1
	v_mul_f32_e32 v2, 0x4f7ffffe, v2
	v_cvt_u32_f32_e32 v2, v2
	v_mul_lo_u32 v3, v3, v2
	v_mul_hi_u32 v3, v2, v3
	v_add_u32_e32 v2, v2, v3
	v_mul_hi_u32 v2, v1, v2
	v_mul_lo_u32 v3, v2, v0
	v_sub_u32_e32 v3, v1, v3
	v_cmp_ge_u32_e32 vcc, v3, v0
	v_add_u32_e32 v4, 1, v2
	v_add_u32_e32 v1, 1, v1
	v_cndmask_b32_e32 v2, v2, v4, vcc
	v_sub_u32_e32 v4, v3, v0
	v_cndmask_b32_e32 v3, v3, v4, vcc
	v_cmp_ge_u32_e32 vcc, v3, v0
	v_add_u32_e32 v3, 1, v2
	s_nop 0
	v_cndmask_b32_e32 v2, v2, v3, vcc
	v_mul_lo_u32 v3, v0, v2
	v_add_u32_e32 v0, v3, v0
	v_cmp_ne_u32_e32 vcc, v1, v0
	v_mov_b64_e32 v[0:1], s[6:7]
	s_and_saveexec_b64 s[6:7], vcc
	s_cbranch_execz .LBB0_193
	v_readlane_b32 s8, v253, 10
	v_readlane_b32 s9, v253, 11
	s_mov_b64 s[10:11], 0
	s_nop 3
	global_load_dword v0, v161, s[8:9] sc1
	s_waitcnt vmcnt(0)
	v_cmp_eq_u32_e32 vcc, v0, v2
	s_and_saveexec_b64 s[8:9], vcc
	s_cbranch_execz .LBB0_192
	s_mov_b32 s20, 1
	s_branch .LBB0_185

;     __device__ __forceinline__ void operator()(const f32x4 (&acc)[2][2][4][2], const Unit& u, int wr, int wc, int fr, int fq) const {
;         const bool isctx = u.pm >= 128;
;         const int v = isctx ? 4 : (u.pm >> 5);
;         const float* bp = isctx ? base_ctx - (size_t)32768 * 1024 : base_lat;
;         float* op = isctx ? out_ctx - (size_t)32768 * 1024 : out_lat;
;         const float* g = gate + v * 6144;
;         const int row0 = u.pm * BM + wr * 64 + fr; const int col0 = u.pn * BM + wc * 32 + 4 * fq;
;         f32x4 gv[2][2];
; #pragma unroll
;         for (int bj = 0; bj < 2; ++bj)
; #pragma unroll
;             for (int n = 0; n < 2; ++n) gv[bj][n] = *(const f32x4*)(g + col0 + bj * HALF + n * 16);
; #pragma unroll
;         for (int ai = 0; ai < 2; ++ai) {
;             f32x4 bs[4][2][2];
; #pragma unroll
;             for (int m = 0; m < 4; ++m) { const size_t off = (size_t)(row0 + ai * HALF + m * 16) * 1024 + col0;
; #pragma unroll
;                 for (int bj = 0; bj < 2; ++bj)
; #pragma unroll
;                     for (int n = 0; n < 2; ++n) bs[m][bj][n] = *(const f32x4*)(bp + off + bj * HALF + n * 16); }
; #pragma unroll
;             for (int m = 0; m < 4; ++m) { const size_t off = (size_t)(row0 + ai * HALF + m * 16) * 1024 + col0;
; #pragma unroll
;                 for (int bj = 0; bj < 2; ++bj)
; #pragma unroll
;                     for (int n = 0; n < 2; ++n) *(f32x4*)(op + off + bj * HALF + n * 16) = bs[m][bj][n] + gv[bj][n] * acc[ai][bj][m][n]; }
.LBB0_472:
	s_lshr_b32 s11, s22, 5
	s_cmpk_gt_i32 s22, 0x7f
	s_mulk_i32 s11, 0x1800
	v_readlane_b32 s48, v252, 17
	s_cselect_b32 s26, 0x6000, s11
	v_readlane_b32 s62, v252, 31
	v_readlane_b32 s11, v254, 12
	v_readlane_b32 s63, v252, 32
	s_cselect_b32 s30, s11, s62
	v_readlane_b32 s11, v254, 13
	s_cselect_b32 s28, s45, s40
	s_cselect_b32 s29, s46, s39
	s_cselect_b32 s31, s11, s63
	s_ashr_i32 s27, s26, 31
	v_lshl_or_b32 v128, s24, 8, v158
	s_lshl_b64 s[26:27], s[26:27], 2
	v_ashrrev_i32_e32 v129, 31, v128
	v_lshl_add_u32 v164, s22, 8, v156
	s_add_u32 s26, s41, s26
	v_lshlrev_b64 v[150:151], 2, v[128:129]
	v_ashrrev_i32_e32 v165, 31, v164
	s_addc_u32 s27, s42, s27
	v_lshl_add_u64 v[152:153], s[28:29], 0, v[150:151]
	v_lshlrev_b64 v[154:155], 12, v[164:165]
	v_lshl_add_u64 v[128:129], s[26:27], 0, v[150:151]
	v_lshl_add_u64 v[166:167], v[152:153], 0, v[154:155]
	global_load_dwordx4 v[140:143], v[128:129], off
	global_load_dwordx4 v[136:139], v[128:129], off offset:64
	global_load_dwordx4 v[132:135], v[128:129], off offset:512
	s_nop 0
	global_load_dwordx4 v[128:131], v[128:129], off offset:576
	s_nop 0
	global_load_dwordx4 v[168:171], v[166:167], off
	global_load_dwordx4 v[172:175], v[166:167], off offset:64
	global_load_dwordx4 v[176:179], v[166:167], off offset:512
	global_load_dwordx4 v[180:183], v[166:167], off offset:576
	v_or_b32_e32 v166, 16, v164
	v_or_b32_e32 v200, 32, v164
	v_ashrrev_i32_e32 v167, 31, v166
	v_ashrrev_i32_e32 v201, 31, v200
	v_lshlrev_b64 v[166:167], 12, v[166:167]
	v_lshlrev_b64 v[232:233], 12, v[200:201]
	v_or_b32_e32 v164, 48, v164
	v_lshl_add_u64 v[196:197], v[152:153], 0, v[166:167]
	v_lshl_add_u64 v[212:213], v[152:153], 0, v[232:233]
	v_ashrrev_i32_e32 v165, 31, v164
	global_load_dwordx4 v[184:187], v[196:197], off
	global_load_dwordx4 v[188:191], v[196:197], off offset:64
	global_load_dwordx4 v[192:195], v[196:197], off offset:512
	s_nop 0
	global_load_dwordx4 v[196:199], v[196:197], off offset:576
	s_nop 0
	global_load_dwordx4 v[200:203], v[212:213], off
	global_load_dwordx4 v[204:207], v[212:213], off offset:64
	global_load_dwordx4 v[208:211], v[212:213], off offset:512
	s_nop 0
	global_load_dwordx4 v[212:215], v[212:213], off offset:576
	v_lshlrev_b64 v[164:165], 12, v[164:165]
	v_lshl_add_u64 v[228:229], v[152:153], 0, v[164:165]
	global_load_dwordx4 v[216:219], v[228:229], off
	global_load_dwordx4 v[220:223], v[228:229], off offset:64
	global_load_dwordx4 v[224:227], v[228:229], off offset:512
	s_nop 0
	global_load_dwordx4 v[228:231], v[228:229], off offset:576
	v_lshl_add_u64 v[150:151], s[30:31], 0, v[150:151]
	v_lshl_add_u64 v[234:235], v[150:151], 0, v[154:155]
	s_mov_b64 s[26:27], 0x80000
	v_lshl_add_u64 v[166:167], v[150:151], 0, v[166:167]
	v_lshl_add_u64 v[232:233], v[150:151], 0, v[232:233]
	v_readlane_b32 s49, v252, 18
	v_readlane_b32 s50, v252, 19
	v_readlane_b32 s51, v252, 20
	v_readlane_b32 s52, v252, 21
	v_readlane_b32 s53, v252, 22
	v_readlane_b32 s54, v252, 23
	v_readlane_b32 s55, v252, 24
	v_readlane_b32 s56, v252, 25
	v_readlane_b32 s57, v252, 26
	v_readlane_b32 s58, v252, 27
	v_readlane_b32 s59, v252, 28
	v_readlane_b32 s60, v252, 29
	v_readlane_b32 s61, v252, 30
	v_readlane_b32 s34, v255, 19
	s_andn2_b64 vcc, exec, s[4:5]
	s_mov_b64 s[4:5], -1
	v_readlane_b32 s48, v252, 1
	v_readlane_b32 s35, v255, 20
	v_readlane_b32 s49, v252, 2
	v_readlane_b32 s50, v252, 3
	v_readlane_b32 s51, v252, 4
	v_readlane_b32 s52, v252, 5
	v_readlane_b32 s53, v252, 6
	v_readlane_b32 s54, v252, 7
	v_readlane_b32 s55, v252, 8
	v_readlane_b32 s56, v252, 9
	v_readlane_b32 s57, v252, 10
	v_readlane_b32 s58, v252, 11
	v_readlane_b32 s59, v252, 12
	v_readlane_b32 s60, v252, 13
	v_readlane_b32 s61, v252, 14
	v_readlane_b32 s62, v252, 15
	v_readlane_b32 s63, v252, 16
	s_waitcnt vmcnt(0)
	v_pk_fma_f32 v[126:127], v[126:127], v[142:143], v[170:171]
	v_pk_fma_f32 v[124:125], v[124:125], v[140:141], v[168:169]
	v_pk_fma_f32 v[122:123], v[122:123], v[138:139], v[174:175]
	v_pk_fma_f32 v[120:121], v[120:121], v[136:137], v[172:173]
	v_pk_fma_f32 v[106:107], v[106:107], v[134:135], v[178:179]
	v_pk_fma_f32 v[104:105], v[104:105], v[132:133], v[176:177]
	v_pk_fma_f32 v[102:103], v[102:103], v[130:131], v[182:183]
	v_pk_fma_f32 v[100:101], v[100:101], v[128:129], v[180:181]
	v_pk_fma_f32 v[118:119], v[118:119], v[142:143], v[186:187]
	v_pk_fma_f32 v[116:117], v[116:117], v[140:141], v[184:185]
	v_pk_fma_f32 v[114:115], v[114:115], v[138:139], v[190:191]
	v_pk_fma_f32 v[84:85], v[84:85], v[132:133], v[208:209]
	v_pk_fma_f32 v[112:113], v[112:113], v[136:137], v[188:189]
	v_pk_fma_f32 v[94:95], v[94:95], v[134:135], v[194:195]
	v_pk_fma_f32 v[92:93], v[92:93], v[132:133], v[192:193]
	v_pk_fma_f32 v[90:91], v[90:91], v[130:131], v[198:199]
	v_pk_fma_f32 v[88:89], v[88:89], v[128:129], v[196:197]
	v_pk_fma_f32 v[110:111], v[110:111], v[142:143], v[202:203]
	v_pk_fma_f32 v[108:109], v[108:109], v[140:141], v[200:201]
	v_pk_fma_f32 v[98:99], v[98:99], v[138:139], v[206:207]
	v_pk_fma_f32 v[96:97], v[96:97], v[136:137], v[204:205]
	v_pk_fma_f32 v[86:87], v[86:87], v[134:135], v[210:211]
	global_store_dwordx4 v[234:235], v[124:127], off sc1
	global_store_dwordx4 v[234:235], v[120:123], off offset:64 sc1
	global_store_dwordx4 v[234:235], v[104:107], off offset:512 sc1
	global_store_dwordx4 v[234:235], v[100:103], off offset:576 sc1
	global_store_dwordx4 v[166:167], v[116:119], off sc1
	global_store_dwordx4 v[166:167], v[112:115], off offset:64 sc1
	global_store_dwordx4 v[166:167], v[92:95], off offset:512 sc1
	global_store_dwordx4 v[166:167], v[88:91], off offset:576 sc1
	global_store_dwordx4 v[232:233], v[108:111], off sc1
;     __device__ __forceinline__ void operator()(const f32x4 (&acc)[2][2][4][2], const Unit& u, int wr, int wc, int fr, int fq) const {
;     ...
;         for (int ai = 0; ai < 2; ++ai) {
;             f32x4 bs[4][2][2];
; #pragma unroll
;             for (int m = 0; m < 4; ++m) { const size_t off = (size_t)(row0 + ai * HALF + m * 16) * 1024 + col0;
; #pragma unroll
;                 for (int bj = 0; bj < 2; ++bj)
; #pragma unroll
;                     for (int n = 0; n < 2; ++n) bs[m][bj][n] = *(const f32x4*)(bp + off + bj * HALF + n * 16); }
; #pragma unroll
;             for (int m = 0; m < 4; ++m) { const size_t off = (size_t)(row0 + ai * HALF + m * 16) * 1024 + col0;
; #pragma unroll
;                 for (int bj = 0; bj < 2; ++bj)
; #pragma unroll
;                     for (int n = 0; n < 2; ++n) *(f32x4*)(op + off + bj * HALF + n * 16) = bs[m][bj][n] + gv[bj][n] * acc[ai][bj][m][n]; }
;             asm volatile("" ::: "memory");
	global_store_dwordx4 v[232:233], v[96:99], off offset:64 sc1
	global_store_dwordx4 v[232:233], v[84:87], off offset:512 sc1
	v_pk_fma_f32 v[74:75], v[74:75], v[130:131], v[214:215]
	v_pk_fma_f32 v[72:73], v[72:73], v[128:129], v[212:213]
	v_lshl_add_u64 v[84:85], v[150:151], 0, v[164:165]
	v_lshl_add_u64 v[164:165], v[154:155], 0, s[26:27]
	s_mov_b64 s[26:27], 0x90000
	global_store_dwordx4 v[232:233], v[72:75], off offset:576 sc1
	v_lshl_add_u64 v[166:167], v[154:155], 0, s[26:27]
	s_mov_b64 s[26:27], 0xa0000
	v_pk_fma_f32 v[74:75], v[82:83], v[142:143], v[218:219]
	v_pk_fma_f32 v[72:73], v[80:81], v[140:141], v[216:217]
	global_store_dwordx4 v[84:85], v[72:75], off sc1
	v_pk_fma_f32 v[70:71], v[70:71], v[134:135], v[226:227]
	v_pk_fma_f32 v[68:69], v[68:69], v[132:133], v[224:225]
	v_pk_fma_f32 v[74:75], v[78:79], v[138:139], v[222:223]
	v_pk_fma_f32 v[72:73], v[76:77], v[136:137], v[220:221]
	v_pk_fma_f32 v[66:67], v[66:67], v[130:131], v[230:231]
	v_pk_fma_f32 v[64:65], v[64:65], v[128:129], v[228:229]
	v_lshl_add_u64 v[168:169], v[154:155], 0, s[26:27]
	s_mov_b64 s[26:27], 0xb0000
	global_store_dwordx4 v[84:85], v[72:75], off offset:64 sc1
	global_store_dwordx4 v[84:85], v[68:71], off offset:512 sc1
	global_store_dwordx4 v[84:85], v[64:67], off offset:576 sc1
	v_lshl_add_u64 v[154:155], v[154:155], 0, s[26:27]
	v_lshl_add_u64 v[76:77], v[152:153], 0, v[164:165]
	v_lshl_add_u64 v[92:93], v[152:153], 0, v[166:167]
	v_lshl_add_u64 v[108:109], v[152:153], 0, v[168:169]
	v_lshl_add_u64 v[124:125], v[152:153], 0, v[154:155]
	global_load_dwordx4 v[64:67], v[76:77], off
	global_load_dwordx4 v[68:71], v[76:77], off offset:64
	global_load_dwordx4 v[72:75], v[76:77], off offset:512
	s_nop 0
	global_load_dwordx4 v[76:79], v[76:77], off offset:576
	s_nop 0
	global_load_dwordx4 v[80:83], v[92:93], off
	global_load_dwordx4 v[84:87], v[92:93], off offset:64
	global_load_dwordx4 v[88:91], v[92:93], off offset:512
	s_nop 0
	global_load_dwordx4 v[92:95], v[92:93], off offset:576
	s_nop 0
	global_load_dwordx4 v[96:99], v[108:109], off
	global_load_dwordx4 v[100:103], v[108:109], off offset:64
	global_load_dwordx4 v[104:107], v[108:109], off offset:512
	s_nop 0
	global_load_dwordx4 v[108:111], v[108:109], off offset:576
	s_nop 0
	global_load_dwordx4 v[112:115], v[124:125], off
	global_load_dwordx4 v[116:119], v[124:125], off offset:64
	global_load_dwordx4 v[120:123], v[124:125], off offset:512
	s_nop 0
	global_load_dwordx4 v[124:127], v[124:125], off offset:576
	v_lshl_add_u64 v[152:153], v[150:151], 0, v[164:165]
	v_lshl_add_u64 v[164:165], v[150:151], 0, v[166:167]
	v_lshl_add_u64 v[166:167], v[150:151], 0, v[168:169]
	v_lshl_add_u64 v[150:151], v[150:151], 0, v[154:155]
	s_waitcnt vmcnt(15)
	v_pk_fma_f32 v[62:63], v[62:63], v[142:143], v[66:67]
	v_pk_fma_f32 v[60:61], v[60:61], v[140:141], v[64:65]
	s_waitcnt vmcnt(14)
	v_pk_fma_f32 v[58:59], v[58:59], v[138:139], v[70:71]
	v_pk_fma_f32 v[56:57], v[56:57], v[136:137], v[68:69]
	s_waitcnt vmcnt(2)
	v_pk_fma_f32 v[10:11], v[10:11], v[138:139], v[118:119]
	v_pk_fma_f32 v[8:9], v[8:9], v[136:137], v[116:117]
	s_waitcnt vmcnt(1)
	v_pk_fma_f32 v[6:7], v[6:7], v[134:135], v[122:123]
	v_pk_fma_f32 v[4:5], v[4:5], v[132:133], v[120:121]
	s_waitcnt vmcnt(0)
	v_pk_fma_f32 v[2:3], v[2:3], v[130:131], v[126:127]
	v_pk_fma_f32 v[0:1], v[0:1], v[128:129], v[124:125]
	v_pk_fma_f32 v[42:43], v[42:43], v[134:135], v[74:75]
	v_pk_fma_f32 v[40:41], v[40:41], v[132:133], v[72:73]
	v_pk_fma_f32 v[34:35], v[34:35], v[130:131], v[78:79]
	v_pk_fma_f32 v[32:33], v[32:33], v[128:129], v[76:77]
	v_pk_fma_f32 v[54:55], v[54:55], v[142:143], v[82:83]
	v_pk_fma_f32 v[52:53], v[52:53], v[140:141], v[80:81]
	v_pk_fma_f32 v[50:51], v[50:51], v[138:139], v[86:87]
	v_pk_fma_f32 v[48:49], v[48:49], v[136:137], v[84:85]
	v_pk_fma_f32 v[26:27], v[26:27], v[134:135], v[90:91]
	v_pk_fma_f32 v[24:25], v[24:25], v[132:133], v[88:89]
	v_pk_fma_f32 v[22:23], v[22:23], v[130:131], v[94:95]
	v_pk_fma_f32 v[20:21], v[20:21], v[128:129], v[92:93]
	v_pk_fma_f32 v[46:47], v[46:47], v[142:143], v[98:99]
	v_pk_fma_f32 v[44:45], v[44:45], v[140:141], v[96:97]
	v_pk_fma_f32 v[38:39], v[38:39], v[138:139], v[102:103]
	v_pk_fma_f32 v[36:37], v[36:37], v[136:137], v[100:101]
	v_pk_fma_f32 v[18:19], v[18:19], v[134:135], v[106:107]
	v_pk_fma_f32 v[16:17], v[16:17], v[132:133], v[104:105]
	v_pk_fma_f32 v[14:15], v[14:15], v[130:131], v[110:111]
	v_pk_fma_f32 v[12:13], v[12:13], v[128:129], v[108:109]
	v_pk_fma_f32 v[30:31], v[30:31], v[142:143], v[114:115]
	v_pk_fma_f32 v[28:29], v[28:29], v[140:141], v[112:113]
	global_store_dwordx4 v[152:153], v[60:63], off sc1
	global_store_dwordx4 v[152:153], v[56:59], off offset:64 sc1
	global_store_dwordx4 v[152:153], v[40:43], off offset:512 sc1
	global_store_dwordx4 v[152:153], v[32:35], off offset:576 sc1
	global_store_dwordx4 v[164:165], v[52:55], off sc1
	global_store_dwordx4 v[164:165], v[48:51], off offset:64 sc1
	global_store_dwordx4 v[164:165], v[24:27], off offset:512 sc1
	global_store_dwordx4 v[164:165], v[20:23], off offset:576 sc1
	global_store_dwordx4 v[166:167], v[44:47], off sc1
	global_store_dwordx4 v[166:167], v[36:39], off offset:64 sc1
	global_store_dwordx4 v[166:167], v[16:19], off offset:512 sc1
	global_store_dwordx4 v[166:167], v[12:15], off offset:576 sc1
	global_store_dwordx4 v[150:151], v[28:31], off sc1
	global_store_dwordx4 v[150:151], v[8:11], off offset:64 sc1
	global_store_dwordx4 v[150:151], v[4:7], off offset:512 sc1
	global_store_dwordx4 v[150:151], v[0:3], off offset:576 sc1
	s_cbranch_vccnz .LBB0_465
	s_andn2_b64 vcc, exec, s[6:7]
	s_cbranch_vccnz .LBB0_464
	s_barrier
	s_branch .LBB0_464

;     __device__ __forceinline__ void operator()(const f32x4 (&acc)[2][2][4][2], const Unit& u, int wr, int wc, int fr, int fq) const {
;         const bool isctx = u.pm >= 128;
;         const int v = isctx ? 4 : (u.pm >> 5);
;         const float* bp = isctx ? base_ctx - (size_t)32768 * 1024 : base_lat;
;         float* op = isctx ? out_ctx - (size_t)32768 * 1024 : out_lat;
;         const float* g = gate + v * 6144;
;         const int row0 = u.pm * BM + wr * 64 + fr; const int col0 = u.pn * BM + wc * 32 + 4 * fq;
;         f32x4 gv[2][2];
; #pragma unroll
;         for (int bj = 0; bj < 2; ++bj)
; #pragma unroll
;             for (int n = 0; n < 2; ++n) gv[bj][n] = *(const f32x4*)(g + col0 + bj * HALF + n * 16);
; #pragma unroll
;         for (int ai = 0; ai < 2; ++ai) {
;             f32x4 bs[4][2][2];
; #pragma unroll
;             for (int m = 0; m < 4; ++m) { const size_t off = (size_t)(row0 + ai * HALF + m * 16) * 1024 + col0;
; #pragma unroll
;                 for (int bj = 0; bj < 2; ++bj)
; #pragma unroll
;                     for (int n = 0; n < 2; ++n) bs[m][bj][n] = *(const f32x4*)(bp + off + bj * HALF + n * 16); }
; #pragma unroll
;             for (int m = 0; m < 4; ++m) { const size_t off = (size_t)(row0 + ai * HALF + m * 16) * 1024 + col0;
; #pragma unroll
;                 for (int bj = 0; bj < 2; ++bj)
; #pragma unroll
;                     for (int n = 0; n < 2; ++n) *(f32x4*)(op + off + bj * HALF + n * 16) = bs[m][bj][n] + gv[bj][n] * acc[ai][bj][m][n]; }
.LBB0_775:
	s_lshr_b32 s16, s40, 5
	v_readlane_b32 s44, v252, 17
	s_cmpk_gt_i32 s40, 0x7f
	s_mulk_i32 s16, 0x1800
	v_readlane_b32 s58, v252, 31
	v_readlane_b32 s17, v254, 12
	s_cselect_b32 s16, 0x6000, s16
	v_readlane_b32 s59, v252, 32
	s_cselect_b32 s18, s17, s58
	v_readlane_b32 s17, v254, 13
	s_cselect_b32 s19, s17, s59
	s_ashr_i32 s17, s16, 31
	s_lshl_b64 s[16:17], s[16:17], 2
	v_lshl_or_b32 v128, s41, 8, v154
	s_add_u32 s16, s33, s16
	v_ashrrev_i32_e32 v129, 31, v128
	v_lshl_add_u32 v164, s40, 8, v152
	s_addc_u32 s17, s34, s17
	v_lshlrev_b64 v[150:151], 2, v[128:129]
	v_ashrrev_i32_e32 v165, 31, v164
	v_lshl_add_u64 v[128:129], s[16:17], 0, v[150:151]
	v_lshl_add_u64 v[166:167], s[18:19], 0, v[150:151]
	v_lshlrev_b64 v[150:151], 12, v[164:165]
	v_or_b32_e32 v180, 16, v164
	v_or_b32_e32 v196, 32, v164
	v_or_b32_e32 v164, 48, v164
	v_ashrrev_i32_e32 v181, 31, v180
	v_ashrrev_i32_e32 v197, 31, v196
	v_ashrrev_i32_e32 v165, 31, v164
	v_lshlrev_b64 v[180:181], 12, v[180:181]
	v_lshlrev_b64 v[196:197], 12, v[196:197]
	v_lshlrev_b64 v[164:165], 12, v[164:165]
	v_lshl_add_u64 v[150:151], v[166:167], 0, v[150:151]
	v_lshl_add_u64 v[228:229], v[166:167], 0, v[180:181]
	v_lshl_add_u64 v[230:231], v[166:167], 0, v[196:197]
	v_lshl_add_u64 v[164:165], v[166:167], 0, v[164:165]
	global_load_dwordx4 v[140:143], v[128:129], off
	global_load_dwordx4 v[136:139], v[128:129], off offset:64
	global_load_dwordx4 v[132:135], v[128:129], off offset:512
	s_nop 0
	global_load_dwordx4 v[128:131], v[128:129], off offset:576
	s_nop 0
	global_load_dwordx4 v[156:159], v[150:151], off
	global_load_dwordx4 v[168:171], v[150:151], off offset:64
	global_load_dwordx4 v[172:175], v[150:151], off offset:512
	global_load_dwordx4 v[176:179], v[150:151], off offset:576
	global_load_dwordx4 v[180:183], v[228:229], off
	global_load_dwordx4 v[184:187], v[228:229], off offset:64
	global_load_dwordx4 v[188:191], v[228:229], off offset:512
	global_load_dwordx4 v[192:195], v[228:229], off offset:576
	global_load_dwordx4 v[196:199], v[230:231], off
	global_load_dwordx4 v[200:203], v[230:231], off offset:64
	global_load_dwordx4 v[204:207], v[230:231], off offset:512
	global_load_dwordx4 v[208:211], v[230:231], off offset:576
	global_load_dwordx4 v[212:215], v[164:165], off
	global_load_dwordx4 v[216:219], v[164:165], off offset:64
	global_load_dwordx4 v[220:223], v[164:165], off offset:512
	global_load_dwordx4 v[224:227], v[164:165], off offset:576
	s_mov_b64 s[16:17], 0x80000
	v_readlane_b32 s45, v252, 18
	v_readlane_b32 s46, v252, 19
	v_readlane_b32 s47, v252, 20
	v_readlane_b32 s48, v252, 21
	v_readlane_b32 s49, v252, 22
	v_readlane_b32 s50, v252, 23
	v_readlane_b32 s51, v252, 24
	v_readlane_b32 s52, v252, 25
	v_readlane_b32 s53, v252, 26
	v_readlane_b32 s54, v252, 27
	v_readlane_b32 s55, v252, 28
	v_readlane_b32 s56, v252, 29
	v_readlane_b32 s57, v252, 30
	s_waitcnt vmcnt(0)
	v_pk_fma_f32 v[124:125], v[124:125], v[140:141], v[156:157]
	v_lshl_add_u64 v[156:157], v[150:151], 0, s[16:17]
	s_mov_b32 s16, 0x80000
	v_pk_fma_f32 v[126:127], v[126:127], v[142:143], v[158:159]
	v_pk_fma_f32 v[74:75], v[74:75], v[138:139], v[218:219]
	v_pk_fma_f32 v[72:73], v[72:73], v[136:137], v[216:217]
	v_pk_fma_f32 v[70:71], v[70:71], v[134:135], v[222:223]
	v_pk_fma_f32 v[68:69], v[68:69], v[132:133], v[220:221]
	v_pk_fma_f32 v[66:67], v[66:67], v[130:131], v[226:227]
	v_pk_fma_f32 v[64:65], v[64:65], v[128:129], v[224:225]
	v_add_co_u32_e32 v158, vcc, s16, v150
	s_mov_b64 s[16:17], 0x90000
	v_pk_fma_f32 v[122:123], v[122:123], v[138:139], v[170:171]
	v_pk_fma_f32 v[120:121], v[120:121], v[136:137], v[168:169]
	v_pk_fma_f32 v[114:115], v[114:115], v[134:135], v[174:175]
	v_pk_fma_f32 v[112:113], v[112:113], v[132:133], v[172:173]
	v_pk_fma_f32 v[106:107], v[106:107], v[130:131], v[178:179]
	v_pk_fma_f32 v[104:105], v[104:105], v[128:129], v[176:177]
	v_pk_fma_f32 v[118:119], v[118:119], v[142:143], v[182:183]
	v_pk_fma_f32 v[116:117], v[116:117], v[140:141], v[180:181]
	v_pk_fma_f32 v[110:111], v[110:111], v[138:139], v[186:187]
	v_pk_fma_f32 v[108:109], v[108:109], v[136:137], v[184:185]
	v_pk_fma_f32 v[98:99], v[98:99], v[134:135], v[190:191]
	v_pk_fma_f32 v[96:97], v[96:97], v[132:133], v[188:189]
	v_pk_fma_f32 v[90:91], v[90:91], v[130:131], v[194:195]
	v_pk_fma_f32 v[88:89], v[88:89], v[128:129], v[192:193]
	v_pk_fma_f32 v[102:103], v[102:103], v[142:143], v[198:199]
	v_pk_fma_f32 v[100:101], v[100:101], v[140:141], v[196:197]
	v_pk_fma_f32 v[94:95], v[94:95], v[138:139], v[202:203]
	v_pk_fma_f32 v[92:93], v[92:93], v[136:137], v[200:201]
	v_pk_fma_f32 v[82:83], v[82:83], v[134:135], v[206:207]
	v_pk_fma_f32 v[80:81], v[80:81], v[132:133], v[204:205]
	v_pk_fma_f32 v[78:79], v[78:79], v[130:131], v[210:211]
	v_pk_fma_f32 v[76:77], v[76:77], v[128:129], v[208:209]
	v_pk_fma_f32 v[86:87], v[86:87], v[142:143], v[214:215]
	v_pk_fma_f32 v[84:85], v[84:85], v[140:141], v[212:213]
	global_store_dwordx4 v[150:151], v[124:127], off sc1
	global_store_dwordx4 v[150:151], v[120:123], off offset:64 sc1
	global_store_dwordx4 v[150:151], v[112:115], off offset:512 sc1
	global_store_dwordx4 v[150:151], v[104:107], off offset:576 sc1
	global_store_dwordx4 v[228:229], v[116:119], off sc1
;     __device__ __forceinline__ void operator()(const f32x4 (&acc)[2][2][4][2], const Unit& u, int wr, int wc, int fr, int fq) const {
;     ...
;             for (int m = 0; m < 4; ++m) { const size_t off = (size_t)(row0 + ai * HALF + m * 16) * 1024 + col0;
; #pragma unroll
;                 for (int bj = 0; bj < 2; ++bj)
; #pragma unroll
;                     for (int n = 0; n < 2; ++n) bs[m][bj][n] = *(const f32x4*)(bp + off + bj * HALF + n * 16); }
; #pragma unroll
;             for (int m = 0; m < 4; ++m) { const size_t off = (size_t)(row0 + ai * HALF + m * 16) * 1024 + col0;
; #pragma unroll
;                 for (int bj = 0; bj < 2; ++bj)
; #pragma unroll
;                     for (int n = 0; n < 2; ++n) *(f32x4*)(op + off + bj * HALF + n * 16) = bs[m][bj][n] + gv[bj][n] * acc[ai][bj][m][n]; }
;             asm volatile("" ::: "memory");
	global_store_dwordx4 v[228:229], v[108:111], off offset:64 sc1
	global_store_dwordx4 v[228:229], v[96:99], off offset:512 sc1
	global_store_dwordx4 v[228:229], v[88:91], off offset:576 sc1
	global_store_dwordx4 v[230:231], v[100:103], off sc1
	global_store_dwordx4 v[230:231], v[92:95], off offset:64 sc1
	global_store_dwordx4 v[230:231], v[80:83], off offset:512 sc1
	global_store_dwordx4 v[230:231], v[76:79], off offset:576 sc1
	global_store_dwordx4 v[164:165], v[84:87], off sc1
	global_store_dwordx4 v[164:165], v[72:75], off offset:64 sc1
	global_store_dwordx4 v[164:165], v[68:71], off offset:512 sc1
	global_store_dwordx4 v[164:165], v[64:67], off offset:576 sc1
	v_addc_co_u32_e32 v159, vcc, 0, v151, vcc
	v_lshl_add_u64 v[164:165], v[150:151], 0, s[16:17]
	s_mov_b32 s16, 0x90000
	v_add_co_u32_e32 v166, vcc, s16, v150
	s_mov_b64 s[16:17], 0xa0000
	s_nop 0
	v_addc_co_u32_e32 v167, vcc, 0, v151, vcc
	v_lshl_add_u64 v[168:169], v[150:151], 0, s[16:17]
	s_mov_b32 s16, 0xa0000
	v_add_co_u32_e32 v170, vcc, s16, v150
	s_mov_b32 s16, 0xb0000
	s_nop 0
	v_addc_co_u32_e32 v171, vcc, 0, v151, vcc
	v_add_co_u32_e32 v172, vcc, s16, v150
	s_mov_b64 s[16:17], 0xb0000
	s_nop 0
	v_addc_co_u32_e32 v173, vcc, 0, v151, vcc
	v_lshl_add_u64 v[150:151], v[150:151], 0, s[16:17]
	global_load_dwordx4 v[64:67], v[156:157], off offset:64
	global_load_dwordx4 v[68:71], v[156:157], off offset:512
	global_load_dwordx4 v[72:75], v[158:159], off
	global_load_dwordx4 v[76:79], v[156:157], off offset:576
	global_load_dwordx4 v[80:83], v[166:167], off
	global_load_dwordx4 v[84:87], v[164:165], off offset:64
	global_load_dwordx4 v[88:91], v[164:165], off offset:512
	global_load_dwordx4 v[92:95], v[164:165], off offset:576
	global_load_dwordx4 v[96:99], v[170:171], off
	global_load_dwordx4 v[100:103], v[168:169], off offset:64
	global_load_dwordx4 v[104:107], v[168:169], off offset:512
	global_load_dwordx4 v[108:111], v[168:169], off offset:576
	global_load_dwordx4 v[112:115], v[172:173], off
	global_load_dwordx4 v[116:119], v[150:151], off offset:64
	global_load_dwordx4 v[120:123], v[150:151], off offset:512
	global_load_dwordx4 v[124:127], v[150:151], off offset:576
	s_and_b64 vcc, exec, s[6:7]
	s_mov_b64 s[6:7], -1
	s_waitcnt vmcnt(15)
	v_pk_fma_f32 v[58:59], v[58:59], v[138:139], v[66:67]
	v_pk_fma_f32 v[56:57], v[56:57], v[136:137], v[64:65]
	s_waitcnt vmcnt(13)
	v_pk_fma_f32 v[62:63], v[62:63], v[142:143], v[74:75]
	v_pk_fma_f32 v[60:61], v[60:61], v[140:141], v[72:73]
	v_pk_fma_f32 v[50:51], v[50:51], v[134:135], v[70:71]
	s_waitcnt vmcnt(2)
	v_pk_fma_f32 v[10:11], v[10:11], v[138:139], v[118:119]
	v_pk_fma_f32 v[18:19], v[18:19], v[142:143], v[114:115]
	v_pk_fma_f32 v[16:17], v[16:17], v[140:141], v[112:113]
	v_pk_fma_f32 v[8:9], v[8:9], v[136:137], v[116:117]
	s_waitcnt vmcnt(1)
	v_pk_fma_f32 v[6:7], v[6:7], v[134:135], v[122:123]
	v_pk_fma_f32 v[4:5], v[4:5], v[132:133], v[120:121]
	s_waitcnt vmcnt(0)
	v_pk_fma_f32 v[2:3], v[2:3], v[130:131], v[126:127]
	v_pk_fma_f32 v[0:1], v[0:1], v[128:129], v[124:125]
	v_pk_fma_f32 v[48:49], v[48:49], v[132:133], v[68:69]
	v_pk_fma_f32 v[42:43], v[42:43], v[130:131], v[78:79]
	v_pk_fma_f32 v[40:41], v[40:41], v[128:129], v[76:77]
	v_pk_fma_f32 v[54:55], v[54:55], v[142:143], v[82:83]
	v_pk_fma_f32 v[52:53], v[52:53], v[140:141], v[80:81]
	v_pk_fma_f32 v[46:47], v[46:47], v[138:139], v[86:87]
	v_pk_fma_f32 v[44:45], v[44:45], v[136:137], v[84:85]
	v_pk_fma_f32 v[34:35], v[34:35], v[134:135], v[90:91]
	v_pk_fma_f32 v[32:33], v[32:33], v[132:133], v[88:89]
	v_pk_fma_f32 v[26:27], v[26:27], v[130:131], v[94:95]
	v_pk_fma_f32 v[24:25], v[24:25], v[128:129], v[92:93]
	v_pk_fma_f32 v[38:39], v[38:39], v[142:143], v[98:99]
	v_pk_fma_f32 v[36:37], v[36:37], v[140:141], v[96:97]
	v_pk_fma_f32 v[30:31], v[30:31], v[138:139], v[102:103]
	v_pk_fma_f32 v[28:29], v[28:29], v[136:137], v[100:101]
	v_pk_fma_f32 v[22:23], v[22:23], v[134:135], v[106:107]
	v_pk_fma_f32 v[20:21], v[20:21], v[132:133], v[104:105]
	v_pk_fma_f32 v[14:15], v[14:15], v[130:131], v[110:111]
	v_pk_fma_f32 v[12:13], v[12:13], v[128:129], v[108:109]
	global_store_dwordx4 v[158:159], v[60:63], off sc1
	global_store_dwordx4 v[156:157], v[56:59], off offset:64 sc1
	global_store_dwordx4 v[156:157], v[48:51], off offset:512 sc1
	global_store_dwordx4 v[156:157], v[40:43], off offset:576 sc1
	global_store_dwordx4 v[166:167], v[52:55], off sc1
	global_store_dwordx4 v[164:165], v[44:47], off offset:64 sc1
	global_store_dwordx4 v[164:165], v[32:35], off offset:512 sc1
	global_store_dwordx4 v[164:165], v[24:27], off offset:576 sc1
	global_store_dwordx4 v[170:171], v[36:39], off sc1
	global_store_dwordx4 v[168:169], v[28:31], off offset:64 sc1
	global_store_dwordx4 v[168:169], v[20:23], off offset:512 sc1
	global_store_dwordx4 v[168:169], v[12:15], off offset:576 sc1
	global_store_dwordx4 v[172:173], v[16:19], off sc1
	global_store_dwordx4 v[150:151], v[8:11], off offset:64 sc1
	global_store_dwordx4 v[150:151], v[4:7], off offset:512 sc1
	global_store_dwordx4 v[150:151], v[0:3], off offset:576 sc1
	s_cbranch_vccnz .LBB0_764
	s_andn2_b64 vcc, exec, s[8:9]
	s_cbranch_vccnz .LBB0_763
	s_barrier
	s_branch .LBB0_763

; __device__ __forceinline__ unsigned xb_ld(unsigned* p)              { return __hip_atomic_load(p, __ATOMIC_RELAXED, __HIP_MEMORY_SCOPE_AGENT); }
; __device__ __forceinline__ unsigned xb_add(unsigned* p, unsigned v) { return __hip_atomic_fetch_add(p, v, __ATOMIC_RELAXED, __HIP_MEMORY_SCOPE_AGENT); }
; #define XB_SPIN(cond, bar) do { unsigned _sp = 0; while (cond) { __builtin_amdgcn_s_sleep(1); \
;     if ((++_sp & 255u) == 0u) { if (xb_ld(&(bar)[XB_TMO])) break; if (_sp > XB_SPIN_CAP) { atomicAdd(&(bar)[XB_TMO], 1u); break; } } } } while (0)
; __device__ __forceinline__ void xcd_barrier(const XcdBarrier& b, int xtid) {
;     asm volatile("s_waitcnt vmcnt(0)" ::: "memory");
;     __syncthreads();
;     if (xtid == 0) {
;         unsigned* bar = b.bar; unsigned bx_ = b.x; asm volatile("" : "+s"(bx_));
;         __builtin_amdgcn_s_waitcnt(0);
;         unsigned nloc = b.st[0], nx = b.st[1];
;         if (nloc == 0u) { xcd_barrier_complete(bar, bx_, nloc, nx); b.st[0] = nloc; b.st[1] = nx; }
;         const unsigned old = xb_add(&bar[XB_XSUB(bx_)], 1u);
;         const unsigned gen = old / nloc;
;         if (old + 1u == (gen + 1u) * nloc) {
;             __builtin_amdgcn_fence(__ATOMIC_RELEASE, "agent");
;             asm volatile("s_waitcnt vmcnt(0)" ::: "memory");
;             const unsigned og = xb_add(&bar[XB_TOP], 1u);
;             const unsigned tg = og / nx;
;             if (og + 1u == (tg + 1u) * nx) xb_add(&bar[XB_TOPGEN], 1u);
;             else XB_SPIN(xb_ld(&bar[XB_TOPGEN]) == tg, bar);
;             __builtin_amdgcn_fence(__ATOMIC_ACQUIRE, "agent");
;             xb_add(&bar[XB_XGEN(bx_)], 1u);
;             asm volatile("s_waitcnt vmcnt(0)" ::: "memory");
;         } else {
;             XB_SPIN(xb_ld(&bar[XB_XGEN(bx_)]) == gen, bar);
;             __builtin_amdgcn_fence(__ATOMIC_ACQUIRE, "agent");
;             asm volatile("s_waitcnt vmcnt(0)" ::: "memory");
;         }
.LBB0_811:
	s_andn2_saveexec_b64 s[6:7], s[6:7]
	s_cbranch_execz .LBB0_54
	s_mov_b64 s[6:7], exec
	s_nop 0
	s_waitcnt lgkmcnt(0)
	s_waitcnt vmcnt(0)
	v_mbcnt_lo_u32_b32 v1, s6, 0
	v_mbcnt_hi_u32_b32 v1, s7, v1
	v_cmp_eq_u32_e32 vcc, 0, v1
	s_and_saveexec_b64 s[8:9], vcc
	s_cbranch_execz .LBB0_814
	s_bcnt1_i32_b64 s6, s[6:7]
	v_mov_b32_e32 v2, s6
	v_readlane_b32 s6, v253, 8
	v_readlane_b32 s7, v253, 9
	s_nop 4
	global_atomic_add v2, v161, v2, s[6:7] sc0
.LBB0_814:
	s_or_b64 exec, exec, s[8:9]
	s_waitcnt vmcnt(0)
	v_readfirstlane_b32 s6, v2
	v_cvt_f32_u32_e32 v2, v0
	v_sub_u32_e32 v3, 0, v0
	v_add_u32_e32 v1, s6, v1
	v_readlane_b32 s6, v253, 10
	v_rcp_iflag_f32_e32 v2, v2
	v_readlane_b32 s7, v253, 11
	s_mov_b64 s[8:9], -1
	v_mul_f32_e32 v2, 0x4f7ffffe, v2
	v_cvt_u32_f32_e32 v2, v2
	v_mul_lo_u32 v3, v3, v2
	v_mul_hi_u32 v3, v2, v3
	v_add_u32_e32 v2, v2, v3
	v_mul_hi_u32 v2, v1, v2
	v_mul_lo_u32 v3, v2, v0
	v_sub_u32_e32 v3, v1, v3
	v_cmp_ge_u32_e32 vcc, v3, v0
	v_add_u32_e32 v4, 1, v2
	v_add_u32_e32 v1, 1, v1
	v_cndmask_b32_e32 v2, v2, v4, vcc
	v_sub_u32_e32 v4, v3, v0
	v_cndmask_b32_e32 v3, v3, v4, vcc
	v_cmp_ge_u32_e32 vcc, v3, v0
	v_add_u32_e32 v3, 1, v2
	s_nop 0
	v_cndmask_b32_e32 v2, v2, v3, vcc
	v_mul_lo_u32 v3, v0, v2
	v_add_u32_e32 v0, v3, v0
	v_cmp_ne_u32_e32 vcc, v1, v0
	v_mov_b64_e32 v[0:1], s[6:7]
	s_and_saveexec_b64 s[6:7], vcc
	s_cbranch_execz .LBB0_826
	v_readlane_b32 s8, v253, 10
	v_readlane_b32 s9, v253, 11
	s_mov_b64 s[10:11], 0
	s_nop 3
	global_load_dword v0, v161, s[8:9] sc1
	s_waitcnt vmcnt(0)
	v_cmp_eq_u32_e32 vcc, v0, v2
	s_and_saveexec_b64 s[8:9], vcc
	s_cbranch_execz .LBB0_825
	s_mov_b32 s20, 1
	s_branch .LBB0_818
